# consumer loop unrolled over the 16-slot ring (immediate LDS addresses); SGU jobs back on the HGRN half (2 per workgroup) since the RWKV half now carries the transposes
# speedup vs baseline: 1.0054x; 1.0054x over previous
; #define LAS __attribute__((address_space(3)))
; #define R4_ISSUE(cc, slot) do { const GAS float* g_ = gp + (size_t)(cc) * 2048; LAS float* l_ = ring + (slot) * 1536; _Pragma("unroll") for (int i_ = 0; i_ < 6; ++i_) \
;         __builtin_amdgcn_global_load_lds((const GAS unsigned*)(g_ + off[i_]), (LAS unsigned*)(l_ + i_ * 256), 16, 0, 0); } while (0)
; #define R4_LOAD(o, sb_) do { const LAS float* sb = (sb_); (o).r = *(const LAS f32x4*)(sb + cgp * 4); (o).w = *(const LAS f32x4*)(sb + 64 + cgp * 4); (o).k = *(const LAS f32x4*)(sb + 128 + cgp * 4); \
;         (o).a = *(const LAS f32x4*)(sb + 256 + cgp * 4); (o).b = *(const LAS f32x4*)(sb + 320 + cgp * 4); (o).vv = sb[192 + rq * 4 + rl]; asm volatile("" ::: "memory"); } while (0)
; __device__ __forceinline__ void rwkv_prompt_wave4(LAS float* ring, const GAS float* RW, int mbase, int h, int rq, GAS float* Sout, GAS float* YR, int lane) {
;     ...
;     for (int ci = 0; ci < NCH; ++ci) {
;         { const int cn = ci + 3; const int cl = cn < NCH ? cn : NCH - 1; R4_ISSUE(cl, cn % R4_NS); }
;         const LAS float* cb = ring + (ci % R4_NS) * 1536; const LAS float* nb = ring + ((ci + 1) % R4_NS) * 1536;
;         R4_LOAD(oC, cb + 768);  R4_STEP(oA, 0);
;         R4_LOAD(oD, cb + 1152); R4_STEP(oB, 1);
;         asm volatile("s_waitcnt vmcnt(12)" ::: "memory");
;         R4_LOAD(oA, nb);        R4_STEP(oC, 2);
;         R4_LOAD(oB, nb + 384);  R4_STEP(oD, 3);
;         if (cgp < 4) YR[(size_t)(mbase + ci * 4 + cgp) * 512 + h * 64 + rq * 4 + rl] = ykeep;
.LBB0_705:
	s_lshl_b32 s0, s15, 2
	s_ashr_i32 s17, s3, 7
	s_and_b32 s24, s0, 0xf0
	s_lshl_b32 s0, s17, 11
	s_bfe_u32 s16, s3, 0x30004
	s_lshl_b32 s82, s16, 8
	s_mov_b32 s21, s83
	v_mov_b32_e32 v71, 0
	v_or_b32_e32 v62, s0, v236
	v_or_b32_e32 v70, s24, v52
	v_mov_b32_e32 v44, 0
	v_mov_b32_e32 v45, v71
	s_lshl_b32 s1, s3, 2
	s_and_b32 s1, s1, 60
	v_or_b32_e32 v59, s1, v65
	v_lshl_add_u32 v42, v59, 2, s14
	s_barrier
	ds_read_b128 v[26:29], v68 offset:1024
	ds_read_b128 v[4:7], v68 offset:256
	ds_read_b128 v[8:11], v68 offset:512
	ds_read_b32 v64, v42 offset:768
	ds_read_b128 v[22:25], v68 offset:1280
	ds_read_b128 v[0:3], v68
	ds_read_b128 v[38:41], v68 offset:2560
	ds_read_b128 v[18:21], v68 offset:1792
	ds_read_b128 v[30:33], v68 offset:2048
	ds_read_b32 v66, v42 offset:2304
	ds_read_b128 v[34:37], v68 offset:2816
	ds_read_b128 v[12:15], v68 offset:1536
	s_mov_b32 s21, 0
	s_mov_b32 s23, 0
	v_add_u32_e32 v46, 0xc000, v67
	v_add_u32_e32 v47, 0xc000, v70
	v_mov_b32_e32 v42, 0
	v_mov_b32_e32 v43, v71
	s_waitcnt lgkmcnt(0)
	s_branch .LBB0_707
.LBB0_707:
	s_cmp_eq_u32 s23, 0
	s_cbranch_scc1 .Lrw_first
	s_waitcnt lgkmcnt(0)
	s_barrier
.Lrw_first:
	s_mov_b32 s23, 1
	s_waitcnt lgkmcnt(8)
	v_pk_mul_f32 v[28:29], v[44:45], v[28:29]
	v_pk_mul_f32 v[8:9], v[64:65], v[8:9] op_sel_hi:[0,1]
	v_pk_fma_f32 v[26:27], v[42:43], v[26:27], v[28:29]
	v_pk_mul_f32 v[10:11], v[64:65], v[10:11] op_sel_hi:[0,1]
	v_add_f32_e32 v26, v26, v27
	ds_read_b128 v[84:87], v67 offset:4096
	v_pk_fma_f32 v[4:5], v[42:43], v[4:5], v[8:9]
	v_add_f32_dpp v26, v26, v26 quad_perm:[1,0,3,2] row_mask:0xf bank_mask:0xf bound_ctrl:1
	ds_read_b128 v[76:79], v67 offset:3328
	v_pk_fma_f32 v[6:7], v[44:45], v[6:7], v[10:11]
	v_add_f32_dpp v26, v26, v26 quad_perm:[2,3,0,1] row_mask:0xf bank_mask:0xf bound_ctrl:1
	ds_read_b128 v[80:83], v67 offset:3584
	ds_read_b32 v108, v70 offset:3840
	v_add_f32_dpp v26, v26, v26 row_half_mirror row_mask:0xf bank_mask:0xf bound_ctrl:1
	ds_read_b128 v[88:91], v67 offset:4352
	ds_read_b128 v[72:75], v67 offset:3072
	v_add_f32_dpp v26, v26, v26 row_mirror row_mask:0xf bank_mask:0xf bound_ctrl:1
	v_pk_fma_f32 v[4:5], v[22:23], v[26:27], v[4:5] op_sel_hi:[1,0,1]
	v_pk_fma_f32 v[6:7], v[24:25], v[26:27], v[6:7] op_sel_hi:[1,0,1]
	s_nop 0
	s_waitcnt lgkmcnt(7)
	v_pk_mul_f32 v[40:41], v[6:7], v[40:41]
	v_pk_mul_f32 v[30:31], v[66:67], v[30:31] op_sel_hi:[0,1]
	v_pk_fma_f32 v[38:39], v[4:5], v[38:39], v[40:41]
	v_pk_mul_f32 v[32:33], v[66:67], v[32:33] op_sel_hi:[0,1]
	v_add_f32_e32 v38, v38, v39
	v_pk_mul_f32 v[2:3], v[2:3], v[6:7]
	v_pk_fma_f32 v[18:19], v[4:5], v[18:19], v[30:31]
	v_add_f32_dpp v38, v38, v38 quad_perm:[1,0,3,2] row_mask:0xf bank_mask:0xf bound_ctrl:1
	ds_read_b128 v[100:103], v67 offset:5632
	v_pk_fma_f32 v[20:21], v[6:7], v[20:21], v[32:33]
	v_add_f32_dpp v38, v38, v38 quad_perm:[2,3,0,1] row_mask:0xf bank_mask:0xf bound_ctrl:1
	v_pk_fma_f32 v[0:1], v[0:1], v[4:5], v[2:3]
	ds_read_b128 v[42:45], v67 offset:4864
	v_add_f32_dpp v38, v38, v38 row_half_mirror row_mask:0xf bank_mask:0xf bound_ctrl:1
	v_add_f32_e32 v0, v0, v1
	ds_write_b32 v50, v0 offset:0
	v_add_f32_dpp v38, v38, v38 row_mirror row_mask:0xf bank_mask:0xf bound_ctrl:1
	v_pk_fma_f32 v[18:19], v[34:35], v[38:39], v[18:19] op_sel_hi:[1,0,1]
	v_pk_fma_f32 v[20:21], v[36:37], v[38:39], v[20:21] op_sel_hi:[1,0,1]
	ds_read_b128 v[96:99], v67 offset:5120
	ds_read_b32 v110, v70 offset:5376
	ds_read_b128 v[104:107], v67 offset:5888
	ds_read_b128 v[92:95], v67 offset:4608
	s_waitcnt lgkmcnt(7)
	v_pk_mul_f32 v[86:87], v[20:21], v[86:87]
	v_pk_mul_f32 v[80:81], v[108:109], v[80:81] op_sel_hi:[0,1]
	v_pk_fma_f32 v[84:85], v[18:19], v[84:85], v[86:87]
	v_pk_mul_f32 v[82:83], v[108:109], v[82:83] op_sel_hi:[0,1]
	v_add_f32_e32 v84, v84, v85
	v_pk_mul_f32 v[14:15], v[14:15], v[20:21]
	v_pk_fma_f32 v[76:77], v[18:19], v[76:77], v[80:81]
	v_add_f32_dpp v84, v84, v84 quad_perm:[1,0,3,2] row_mask:0xf bank_mask:0xf bound_ctrl:1
	ds_read_b128 v[26:29], v67 offset:7168
	v_pk_fma_f32 v[78:79], v[20:21], v[78:79], v[82:83]
	v_add_f32_dpp v84, v84, v84 quad_perm:[2,3,0,1] row_mask:0xf bank_mask:0xf bound_ctrl:1
	v_pk_fma_f32 v[12:13], v[12:13], v[18:19], v[14:15]
	ds_read_b128 v[4:7], v67 offset:6400
	v_add_f32_dpp v84, v84, v84 row_half_mirror row_mask:0xf bank_mask:0xf bound_ctrl:1
	v_add_f32_e32 v12, v12, v13
	ds_write_b32 v50, v12 offset:256
	v_add_f32_dpp v84, v84, v84 row_mirror row_mask:0xf bank_mask:0xf bound_ctrl:1
	v_pk_fma_f32 v[76:77], v[88:89], v[84:85], v[76:77] op_sel_hi:[1,0,1]
	v_pk_fma_f32 v[78:79], v[90:91], v[84:85], v[78:79] op_sel_hi:[1,0,1]
	ds_read_b128 v[8:11], v67 offset:6656
	ds_read_b32 v64, v70 offset:6912
	ds_read_b128 v[22:25], v67 offset:7424
	ds_read_b128 v[0:3], v67 offset:6144
	s_waitcnt lgkmcnt(7)
	v_pk_mul_f32 v[102:103], v[78:79], v[102:103]
	v_pk_mul_f32 v[96:97], v[110:111], v[96:97] op_sel_hi:[0,1]
	v_pk_fma_f32 v[100:101], v[76:77], v[100:101], v[102:103]
	v_pk_mul_f32 v[98:99], v[110:111], v[98:99] op_sel_hi:[0,1]
	v_add_f32_e32 v100, v100, v101
	v_pk_mul_f32 v[74:75], v[74:75], v[78:79]
	v_pk_fma_f32 v[42:43], v[76:77], v[42:43], v[96:97]
	v_add_f32_dpp v100, v100, v100 quad_perm:[1,0,3,2] row_mask:0xf bank_mask:0xf bound_ctrl:1
	ds_read_b128 v[38:41], v67 offset:8704
	v_pk_fma_f32 v[44:45], v[78:79], v[44:45], v[98:99]
	v_add_f32_dpp v100, v100, v100 quad_perm:[2,3,0,1] row_mask:0xf bank_mask:0xf bound_ctrl:1
	v_pk_fma_f32 v[72:73], v[72:73], v[76:77], v[74:75]
	ds_read_b128 v[18:21], v67 offset:7936
	v_add_f32_dpp v100, v100, v100 row_half_mirror row_mask:0xf bank_mask:0xf bound_ctrl:1
	v_add_f32_e32 v72, v72, v73
	ds_write_b32 v50, v72 offset:512
	v_add_f32_dpp v100, v100, v100 row_mirror row_mask:0xf bank_mask:0xf bound_ctrl:1
	v_pk_fma_f32 v[42:43], v[104:105], v[100:101], v[42:43] op_sel_hi:[1,0,1]
	v_pk_fma_f32 v[44:45], v[106:107], v[100:101], v[44:45] op_sel_hi:[1,0,1]
	ds_read_b128 v[30:33], v67 offset:8192
	ds_read_b32 v66, v70 offset:8448
	ds_read_b128 v[34:37], v67 offset:8960
	ds_read_b128 v[12:15], v67 offset:7680
	v_pk_mul_f32 v[94:95], v[94:95], v[44:45]
	s_nop 0
	v_pk_fma_f32 v[92:93], v[92:93], v[42:43], v[94:95]
	s_nop 0
	v_add_f32_e32 v92, v92, v93
	ds_write_b32 v50, v92 offset:768
	s_waitcnt lgkmcnt(8)
; #define LAS __attribute__((address_space(3)))
; #define R4_ISSUE(cc, slot) do { const GAS float* g_ = gp + (size_t)(cc) * 2048; LAS float* l_ = ring + (slot) * 1536; _Pragma("unroll") for (int i_ = 0; i_ < 6; ++i_) \
;         __builtin_amdgcn_global_load_lds((const GAS unsigned*)(g_ + off[i_]), (LAS unsigned*)(l_ + i_ * 256), 16, 0, 0); } while (0)
; #define R4_LOAD(o, sb_) do { const LAS float* sb = (sb_); (o).r = *(const LAS f32x4*)(sb + cgp * 4); (o).w = *(const LAS f32x4*)(sb + 64 + cgp * 4); (o).k = *(const LAS f32x4*)(sb + 128 + cgp * 4); \
;         (o).a = *(const LAS f32x4*)(sb + 256 + cgp * 4); (o).b = *(const LAS f32x4*)(sb + 320 + cgp * 4); (o).vv = sb[192 + rq * 4 + rl]; asm volatile("" ::: "memory"); } while (0)
; __device__ __forceinline__ void rwkv_prompt_wave4(LAS float* ring, const GAS float* RW, int mbase, int h, int rq, GAS float* Sout, GAS float* YR, int lane) {
;     ...
;     for (int ci = 0; ci < NCH; ++ci) {
;         { const int cn = ci + 3; const int cl = cn < NCH ? cn : NCH - 1; R4_ISSUE(cl, cn % R4_NS); }
;         const LAS float* cb = ring + (ci % R4_NS) * 1536; const LAS float* nb = ring + ((ci + 1) % R4_NS) * 1536;
;         R4_LOAD(oC, cb + 768);  R4_STEP(oA, 0);
;         R4_LOAD(oD, cb + 1152); R4_STEP(oB, 1);
;         asm volatile("s_waitcnt vmcnt(12)" ::: "memory");
;         R4_LOAD(oA, nb);        R4_STEP(oC, 2);
;         R4_LOAD(oB, nb + 384);  R4_STEP(oD, 3);
;         if (cgp < 4) YR[(size_t)(mbase + ci * 4 + cgp) * 512 + h * 64 + rq * 4 + rl] = ykeep;
	v_pk_mul_f32 v[28:29], v[44:45], v[28:29]
	v_pk_mul_f32 v[8:9], v[64:65], v[8:9] op_sel_hi:[0,1]
	v_pk_fma_f32 v[26:27], v[42:43], v[26:27], v[28:29]
	v_pk_mul_f32 v[10:11], v[64:65], v[10:11] op_sel_hi:[0,1]
	v_add_f32_e32 v26, v26, v27
	ds_read_b128 v[84:87], v67 offset:10240
	v_pk_fma_f32 v[4:5], v[42:43], v[4:5], v[8:9]
	v_add_f32_dpp v26, v26, v26 quad_perm:[1,0,3,2] row_mask:0xf bank_mask:0xf bound_ctrl:1
	ds_read_b128 v[76:79], v67 offset:9472
	v_pk_fma_f32 v[6:7], v[44:45], v[6:7], v[10:11]
	v_add_f32_dpp v26, v26, v26 quad_perm:[2,3,0,1] row_mask:0xf bank_mask:0xf bound_ctrl:1
	ds_read_b128 v[80:83], v67 offset:9728
	ds_read_b32 v108, v70 offset:9984
	v_add_f32_dpp v26, v26, v26 row_half_mirror row_mask:0xf bank_mask:0xf bound_ctrl:1
	ds_read_b128 v[88:91], v67 offset:10496
	ds_read_b128 v[72:75], v67 offset:9216
	v_add_f32_dpp v26, v26, v26 row_mirror row_mask:0xf bank_mask:0xf bound_ctrl:1
	v_pk_fma_f32 v[4:5], v[22:23], v[26:27], v[4:5] op_sel_hi:[1,0,1]
	v_pk_fma_f32 v[6:7], v[24:25], v[26:27], v[6:7] op_sel_hi:[1,0,1]
	s_nop 0
	s_waitcnt lgkmcnt(7)
	v_pk_mul_f32 v[40:41], v[6:7], v[40:41]
	v_pk_mul_f32 v[30:31], v[66:67], v[30:31] op_sel_hi:[0,1]
	v_pk_fma_f32 v[38:39], v[4:5], v[38:39], v[40:41]
	v_pk_mul_f32 v[32:33], v[66:67], v[32:33] op_sel_hi:[0,1]
	v_add_f32_e32 v38, v38, v39
	v_pk_mul_f32 v[2:3], v[2:3], v[6:7]
	v_pk_fma_f32 v[18:19], v[4:5], v[18:19], v[30:31]
	v_add_f32_dpp v38, v38, v38 quad_perm:[1,0,3,2] row_mask:0xf bank_mask:0xf bound_ctrl:1
	ds_read_b128 v[100:103], v67 offset:11776
	v_pk_fma_f32 v[20:21], v[6:7], v[20:21], v[32:33]
	v_add_f32_dpp v38, v38, v38 quad_perm:[2,3,0,1] row_mask:0xf bank_mask:0xf bound_ctrl:1
	v_pk_fma_f32 v[0:1], v[0:1], v[4:5], v[2:3]
	ds_read_b128 v[42:45], v67 offset:11008
	v_add_f32_dpp v38, v38, v38 row_half_mirror row_mask:0xf bank_mask:0xf bound_ctrl:1
	v_add_f32_e32 v0, v0, v1
	ds_write_b32 v50, v0 offset:1024
	v_add_f32_dpp v38, v38, v38 row_mirror row_mask:0xf bank_mask:0xf bound_ctrl:1
	v_pk_fma_f32 v[18:19], v[34:35], v[38:39], v[18:19] op_sel_hi:[1,0,1]
	v_pk_fma_f32 v[20:21], v[36:37], v[38:39], v[20:21] op_sel_hi:[1,0,1]
	ds_read_b128 v[96:99], v67 offset:11264
	ds_read_b32 v110, v70 offset:11520
	ds_read_b128 v[104:107], v67 offset:12032
	ds_read_b128 v[92:95], v67 offset:10752
	s_waitcnt lgkmcnt(7)
	v_pk_mul_f32 v[86:87], v[20:21], v[86:87]
	v_pk_mul_f32 v[80:81], v[108:109], v[80:81] op_sel_hi:[0,1]
	v_pk_fma_f32 v[84:85], v[18:19], v[84:85], v[86:87]
	v_pk_mul_f32 v[82:83], v[108:109], v[82:83] op_sel_hi:[0,1]
	v_add_f32_e32 v84, v84, v85
	v_pk_mul_f32 v[14:15], v[14:15], v[20:21]
	v_pk_fma_f32 v[76:77], v[18:19], v[76:77], v[80:81]
	v_add_f32_dpp v84, v84, v84 quad_perm:[1,0,3,2] row_mask:0xf bank_mask:0xf bound_ctrl:1
	ds_read_b128 v[26:29], v67 offset:13312
	v_pk_fma_f32 v[78:79], v[20:21], v[78:79], v[82:83]
	v_add_f32_dpp v84, v84, v84 quad_perm:[2,3,0,1] row_mask:0xf bank_mask:0xf bound_ctrl:1
	v_pk_fma_f32 v[12:13], v[12:13], v[18:19], v[14:15]
	ds_read_b128 v[4:7], v67 offset:12544
	v_add_f32_dpp v84, v84, v84 row_half_mirror row_mask:0xf bank_mask:0xf bound_ctrl:1
	v_add_f32_e32 v12, v12, v13
	ds_write_b32 v50, v12 offset:1280
	v_add_f32_dpp v84, v84, v84 row_mirror row_mask:0xf bank_mask:0xf bound_ctrl:1
	v_pk_fma_f32 v[76:77], v[88:89], v[84:85], v[76:77] op_sel_hi:[1,0,1]
	v_pk_fma_f32 v[78:79], v[90:91], v[84:85], v[78:79] op_sel_hi:[1,0,1]
	ds_read_b128 v[8:11], v67 offset:12800
	ds_read_b32 v64, v70 offset:13056
	ds_read_b128 v[22:25], v67 offset:13568
	ds_read_b128 v[0:3], v67 offset:12288
	s_waitcnt lgkmcnt(7)
	v_pk_mul_f32 v[102:103], v[78:79], v[102:103]
	v_pk_mul_f32 v[96:97], v[110:111], v[96:97] op_sel_hi:[0,1]
	v_pk_fma_f32 v[100:101], v[76:77], v[100:101], v[102:103]
	v_pk_mul_f32 v[98:99], v[110:111], v[98:99] op_sel_hi:[0,1]
	v_add_f32_e32 v100, v100, v101
	v_pk_mul_f32 v[74:75], v[74:75], v[78:79]
	v_pk_fma_f32 v[42:43], v[76:77], v[42:43], v[96:97]
	v_add_f32_dpp v100, v100, v100 quad_perm:[1,0,3,2] row_mask:0xf bank_mask:0xf bound_ctrl:1
	ds_read_b128 v[38:41], v67 offset:14848
	v_pk_fma_f32 v[44:45], v[78:79], v[44:45], v[98:99]
	v_add_f32_dpp v100, v100, v100 quad_perm:[2,3,0,1] row_mask:0xf bank_mask:0xf bound_ctrl:1
	v_pk_fma_f32 v[72:73], v[72:73], v[76:77], v[74:75]
	ds_read_b128 v[18:21], v67 offset:14080
	v_add_f32_dpp v100, v100, v100 row_half_mirror row_mask:0xf bank_mask:0xf bound_ctrl:1
	v_add_f32_e32 v72, v72, v73
	ds_write_b32 v50, v72 offset:1536
	v_add_f32_dpp v100, v100, v100 row_mirror row_mask:0xf bank_mask:0xf bound_ctrl:1
	v_pk_fma_f32 v[42:43], v[104:105], v[100:101], v[42:43] op_sel_hi:[1,0,1]
	v_pk_fma_f32 v[44:45], v[106:107], v[100:101], v[44:45] op_sel_hi:[1,0,1]
	ds_read_b128 v[30:33], v67 offset:14336
	ds_read_b32 v66, v70 offset:14592
	ds_read_b128 v[34:37], v67 offset:15104
	ds_read_b128 v[12:15], v67 offset:13824
	v_pk_mul_f32 v[94:95], v[94:95], v[44:45]
	s_nop 0
	v_pk_fma_f32 v[92:93], v[92:93], v[42:43], v[94:95]
	s_nop 0
	v_add_f32_e32 v92, v92, v93
	ds_write_b32 v50, v92 offset:1792
	s_waitcnt lgkmcnt(8)
	v_pk_mul_f32 v[28:29], v[44:45], v[28:29]
	v_pk_mul_f32 v[8:9], v[64:65], v[8:9] op_sel_hi:[0,1]
	v_pk_fma_f32 v[26:27], v[42:43], v[26:27], v[28:29]
	v_pk_mul_f32 v[10:11], v[64:65], v[10:11] op_sel_hi:[0,1]
	v_add_f32_e32 v26, v26, v27
	ds_read_b128 v[84:87], v67 offset:16384
	v_pk_fma_f32 v[4:5], v[42:43], v[4:5], v[8:9]
	v_add_f32_dpp v26, v26, v26 quad_perm:[1,0,3,2] row_mask:0xf bank_mask:0xf bound_ctrl:1
	ds_read_b128 v[76:79], v67 offset:15616
	v_pk_fma_f32 v[6:7], v[44:45], v[6:7], v[10:11]
	v_add_f32_dpp v26, v26, v26 quad_perm:[2,3,0,1] row_mask:0xf bank_mask:0xf bound_ctrl:1
	ds_read_b128 v[80:83], v67 offset:15872
	ds_read_b32 v108, v70 offset:16128
	v_add_f32_dpp v26, v26, v26 row_half_mirror row_mask:0xf bank_mask:0xf bound_ctrl:1
	ds_read_b128 v[88:91], v67 offset:16640
	ds_read_b128 v[72:75], v67 offset:15360
	v_add_f32_dpp v26, v26, v26 row_mirror row_mask:0xf bank_mask:0xf bound_ctrl:1
	v_pk_fma_f32 v[4:5], v[22:23], v[26:27], v[4:5] op_sel_hi:[1,0,1]
	v_pk_fma_f32 v[6:7], v[24:25], v[26:27], v[6:7] op_sel_hi:[1,0,1]
	s_nop 0
	s_waitcnt lgkmcnt(7)
; #define LAS __attribute__((address_space(3)))
; #define R4_ISSUE(cc, slot) do { const GAS float* g_ = gp + (size_t)(cc) * 2048; LAS float* l_ = ring + (slot) * 1536; _Pragma("unroll") for (int i_ = 0; i_ < 6; ++i_) \
;         __builtin_amdgcn_global_load_lds((const GAS unsigned*)(g_ + off[i_]), (LAS unsigned*)(l_ + i_ * 256), 16, 0, 0); } while (0)
; #define R4_LOAD(o, sb_) do { const LAS float* sb = (sb_); (o).r = *(const LAS f32x4*)(sb + cgp * 4); (o).w = *(const LAS f32x4*)(sb + 64 + cgp * 4); (o).k = *(const LAS f32x4*)(sb + 128 + cgp * 4); \
;         (o).a = *(const LAS f32x4*)(sb + 256 + cgp * 4); (o).b = *(const LAS f32x4*)(sb + 320 + cgp * 4); (o).vv = sb[192 + rq * 4 + rl]; asm volatile("" ::: "memory"); } while (0)
; __device__ __forceinline__ void rwkv_prompt_wave4(LAS float* ring, const GAS float* RW, int mbase, int h, int rq, GAS float* Sout, GAS float* YR, int lane) {
;     ...
;     for (int cc = 0; cc < 3; ++cc) R4_ISSUE(cc, cc);
;     float ykeep = 0.f;
;     R4Ops oA, oB, oC, oD;
;     asm volatile("s_waitcnt vmcnt(12)" ::: "memory");
;     R4_LOAD(oA, ring); R4_LOAD(oB, ring + 384);
;     for (int ci = 0; ci < NCH; ++ci) {
;         { const int cn = ci + 3; const int cl = cn < NCH ? cn : NCH - 1; R4_ISSUE(cl, cn % R4_NS); }
;         const LAS float* cb = ring + (ci % R4_NS) * 1536; const LAS float* nb = ring + ((ci + 1) % R4_NS) * 1536;
;         R4_LOAD(oC, cb + 768);  R4_STEP(oA, 0);
;         R4_LOAD(oD, cb + 1152); R4_STEP(oB, 1);
;         asm volatile("s_waitcnt vmcnt(12)" ::: "memory");
;         R4_LOAD(oA, nb);        R4_STEP(oC, 2);
;         R4_LOAD(oB, nb + 384);  R4_STEP(oD, 3);
;         if (cgp < 4) YR[(size_t)(mbase + ci * 4 + cgp) * 512 + h * 64 + rq * 4 + rl] = ykeep;
;     }
	v_pk_mul_f32 v[40:41], v[6:7], v[40:41]
	v_pk_mul_f32 v[30:31], v[66:67], v[30:31] op_sel_hi:[0,1]
	v_pk_fma_f32 v[38:39], v[4:5], v[38:39], v[40:41]
	v_pk_mul_f32 v[32:33], v[66:67], v[32:33] op_sel_hi:[0,1]
	v_add_f32_e32 v38, v38, v39
	v_pk_mul_f32 v[2:3], v[2:3], v[6:7]
	v_pk_fma_f32 v[18:19], v[4:5], v[18:19], v[30:31]
	v_add_f32_dpp v38, v38, v38 quad_perm:[1,0,3,2] row_mask:0xf bank_mask:0xf bound_ctrl:1
	ds_read_b128 v[100:103], v67 offset:17920
	v_pk_fma_f32 v[20:21], v[6:7], v[20:21], v[32:33]
	v_add_f32_dpp v38, v38, v38 quad_perm:[2,3,0,1] row_mask:0xf bank_mask:0xf bound_ctrl:1
	v_pk_fma_f32 v[0:1], v[0:1], v[4:5], v[2:3]
	ds_read_b128 v[42:45], v67 offset:17152
	v_add_f32_dpp v38, v38, v38 row_half_mirror row_mask:0xf bank_mask:0xf bound_ctrl:1
	v_add_f32_e32 v0, v0, v1
	ds_write_b32 v50, v0 offset:2048
	v_add_f32_dpp v38, v38, v38 row_mirror row_mask:0xf bank_mask:0xf bound_ctrl:1
	v_pk_fma_f32 v[18:19], v[34:35], v[38:39], v[18:19] op_sel_hi:[1,0,1]
	v_pk_fma_f32 v[20:21], v[36:37], v[38:39], v[20:21] op_sel_hi:[1,0,1]
	ds_read_b128 v[96:99], v67 offset:17408
	ds_read_b32 v110, v70 offset:17664
	ds_read_b128 v[104:107], v67 offset:18176
	ds_read_b128 v[92:95], v67 offset:16896
	s_waitcnt lgkmcnt(7)
	v_pk_mul_f32 v[86:87], v[20:21], v[86:87]
	v_pk_mul_f32 v[80:81], v[108:109], v[80:81] op_sel_hi:[0,1]
	v_pk_fma_f32 v[84:85], v[18:19], v[84:85], v[86:87]
	v_pk_mul_f32 v[82:83], v[108:109], v[82:83] op_sel_hi:[0,1]
	v_add_f32_e32 v84, v84, v85
	v_pk_mul_f32 v[14:15], v[14:15], v[20:21]
	v_pk_fma_f32 v[76:77], v[18:19], v[76:77], v[80:81]
	v_add_f32_dpp v84, v84, v84 quad_perm:[1,0,3,2] row_mask:0xf bank_mask:0xf bound_ctrl:1
	ds_read_b128 v[26:29], v67 offset:19456
	v_pk_fma_f32 v[78:79], v[20:21], v[78:79], v[82:83]
	v_add_f32_dpp v84, v84, v84 quad_perm:[2,3,0,1] row_mask:0xf bank_mask:0xf bound_ctrl:1
	v_pk_fma_f32 v[12:13], v[12:13], v[18:19], v[14:15]
	ds_read_b128 v[4:7], v67 offset:18688
	v_add_f32_dpp v84, v84, v84 row_half_mirror row_mask:0xf bank_mask:0xf bound_ctrl:1
	v_add_f32_e32 v12, v12, v13
	ds_write_b32 v50, v12 offset:2304
	v_add_f32_dpp v84, v84, v84 row_mirror row_mask:0xf bank_mask:0xf bound_ctrl:1
	v_pk_fma_f32 v[76:77], v[88:89], v[84:85], v[76:77] op_sel_hi:[1,0,1]
	v_pk_fma_f32 v[78:79], v[90:91], v[84:85], v[78:79] op_sel_hi:[1,0,1]
	ds_read_b128 v[8:11], v67 offset:18944
	ds_read_b32 v64, v70 offset:19200
	ds_read_b128 v[22:25], v67 offset:19712
	ds_read_b128 v[0:3], v67 offset:18432
	s_waitcnt lgkmcnt(7)
	v_pk_mul_f32 v[102:103], v[78:79], v[102:103]
	v_pk_mul_f32 v[96:97], v[110:111], v[96:97] op_sel_hi:[0,1]
	v_pk_fma_f32 v[100:101], v[76:77], v[100:101], v[102:103]
	v_pk_mul_f32 v[98:99], v[110:111], v[98:99] op_sel_hi:[0,1]
	v_add_f32_e32 v100, v100, v101
	v_pk_mul_f32 v[74:75], v[74:75], v[78:79]
	v_pk_fma_f32 v[42:43], v[76:77], v[42:43], v[96:97]
	v_add_f32_dpp v100, v100, v100 quad_perm:[1,0,3,2] row_mask:0xf bank_mask:0xf bound_ctrl:1
	ds_read_b128 v[38:41], v67 offset:20992
	v_pk_fma_f32 v[44:45], v[78:79], v[44:45], v[98:99]
	v_add_f32_dpp v100, v100, v100 quad_perm:[2,3,0,1] row_mask:0xf bank_mask:0xf bound_ctrl:1
	v_pk_fma_f32 v[72:73], v[72:73], v[76:77], v[74:75]
	ds_read_b128 v[18:21], v67 offset:20224
	v_add_f32_dpp v100, v100, v100 row_half_mirror row_mask:0xf bank_mask:0xf bound_ctrl:1
	v_add_f32_e32 v72, v72, v73
	ds_write_b32 v50, v72 offset:2560
	v_add_f32_dpp v100, v100, v100 row_mirror row_mask:0xf bank_mask:0xf bound_ctrl:1
	v_pk_fma_f32 v[42:43], v[104:105], v[100:101], v[42:43] op_sel_hi:[1,0,1]
	v_pk_fma_f32 v[44:45], v[106:107], v[100:101], v[44:45] op_sel_hi:[1,0,1]
	ds_read_b128 v[30:33], v67 offset:20480
	ds_read_b32 v66, v70 offset:20736
	ds_read_b128 v[34:37], v67 offset:21248
	ds_read_b128 v[12:15], v67 offset:19968
	v_pk_mul_f32 v[94:95], v[94:95], v[44:45]
	s_nop 0
	v_pk_fma_f32 v[92:93], v[92:93], v[42:43], v[94:95]
	s_nop 0
	v_add_f32_e32 v92, v92, v93
	ds_write_b32 v50, v92 offset:2816
	s_waitcnt lgkmcnt(8)
	v_pk_mul_f32 v[28:29], v[44:45], v[28:29]
	v_pk_mul_f32 v[8:9], v[64:65], v[8:9] op_sel_hi:[0,1]
	v_pk_fma_f32 v[26:27], v[42:43], v[26:27], v[28:29]
	v_pk_mul_f32 v[10:11], v[64:65], v[10:11] op_sel_hi:[0,1]
	v_add_f32_e32 v26, v26, v27
	ds_read_b128 v[84:87], v67 offset:22528
	v_pk_fma_f32 v[4:5], v[42:43], v[4:5], v[8:9]
	v_add_f32_dpp v26, v26, v26 quad_perm:[1,0,3,2] row_mask:0xf bank_mask:0xf bound_ctrl:1
	ds_read_b128 v[76:79], v67 offset:21760
	v_pk_fma_f32 v[6:7], v[44:45], v[6:7], v[10:11]
	v_add_f32_dpp v26, v26, v26 quad_perm:[2,3,0,1] row_mask:0xf bank_mask:0xf bound_ctrl:1
	ds_read_b128 v[80:83], v67 offset:22016
	ds_read_b32 v108, v70 offset:22272
	v_add_f32_dpp v26, v26, v26 row_half_mirror row_mask:0xf bank_mask:0xf bound_ctrl:1
	ds_read_b128 v[88:91], v67 offset:22784
	ds_read_b128 v[72:75], v67 offset:21504
	v_add_f32_dpp v26, v26, v26 row_mirror row_mask:0xf bank_mask:0xf bound_ctrl:1
	v_pk_fma_f32 v[4:5], v[22:23], v[26:27], v[4:5] op_sel_hi:[1,0,1]
	v_pk_fma_f32 v[6:7], v[24:25], v[26:27], v[6:7] op_sel_hi:[1,0,1]
	s_nop 0
	s_waitcnt lgkmcnt(7)
; #define LAS __attribute__((address_space(3)))
; #define R4_ISSUE(cc, slot) do { const GAS float* g_ = gp + (size_t)(cc) * 2048; LAS float* l_ = ring + (slot) * 1536; _Pragma("unroll") for (int i_ = 0; i_ < 6; ++i_) \
;         __builtin_amdgcn_global_load_lds((const GAS unsigned*)(g_ + off[i_]), (LAS unsigned*)(l_ + i_ * 256), 16, 0, 0); } while (0)
; #define R4_LOAD(o, sb_) do { const LAS float* sb = (sb_); (o).r = *(const LAS f32x4*)(sb + cgp * 4); (o).w = *(const LAS f32x4*)(sb + 64 + cgp * 4); (o).k = *(const LAS f32x4*)(sb + 128 + cgp * 4); \
;         (o).a = *(const LAS f32x4*)(sb + 256 + cgp * 4); (o).b = *(const LAS f32x4*)(sb + 320 + cgp * 4); (o).vv = sb[192 + rq * 4 + rl]; asm volatile("" ::: "memory"); } while (0)
; __device__ __forceinline__ void rwkv_prompt_wave4(LAS float* ring, const GAS float* RW, int mbase, int h, int rq, GAS float* Sout, GAS float* YR, int lane) {
;     ...
;     for (int cc = 0; cc < 3; ++cc) R4_ISSUE(cc, cc);
;     float ykeep = 0.f;
;     R4Ops oA, oB, oC, oD;
;     asm volatile("s_waitcnt vmcnt(12)" ::: "memory");
;     R4_LOAD(oA, ring); R4_LOAD(oB, ring + 384);
;     for (int ci = 0; ci < NCH; ++ci) {
;         { const int cn = ci + 3; const int cl = cn < NCH ? cn : NCH - 1; R4_ISSUE(cl, cn % R4_NS); }
;         const LAS float* cb = ring + (ci % R4_NS) * 1536; const LAS float* nb = ring + ((ci + 1) % R4_NS) * 1536;
;         R4_LOAD(oC, cb + 768);  R4_STEP(oA, 0);
;         R4_LOAD(oD, cb + 1152); R4_STEP(oB, 1);
;         asm volatile("s_waitcnt vmcnt(12)" ::: "memory");
;         R4_LOAD(oA, nb);        R4_STEP(oC, 2);
;         R4_LOAD(oB, nb + 384);  R4_STEP(oD, 3);
;         if (cgp < 4) YR[(size_t)(mbase + ci * 4 + cgp) * 512 + h * 64 + rq * 4 + rl] = ykeep;
;     }
	v_pk_mul_f32 v[40:41], v[6:7], v[40:41]
	v_pk_mul_f32 v[30:31], v[66:67], v[30:31] op_sel_hi:[0,1]
	v_pk_fma_f32 v[38:39], v[4:5], v[38:39], v[40:41]
	v_pk_mul_f32 v[32:33], v[66:67], v[32:33] op_sel_hi:[0,1]
	v_add_f32_e32 v38, v38, v39
	v_pk_mul_f32 v[2:3], v[2:3], v[6:7]
	v_pk_fma_f32 v[18:19], v[4:5], v[18:19], v[30:31]
	v_add_f32_dpp v38, v38, v38 quad_perm:[1,0,3,2] row_mask:0xf bank_mask:0xf bound_ctrl:1
	ds_read_b128 v[100:103], v67 offset:24064
	v_pk_fma_f32 v[20:21], v[6:7], v[20:21], v[32:33]
	v_add_f32_dpp v38, v38, v38 quad_perm:[2,3,0,1] row_mask:0xf bank_mask:0xf bound_ctrl:1
	v_pk_fma_f32 v[0:1], v[0:1], v[4:5], v[2:3]
	ds_read_b128 v[42:45], v67 offset:23296
	v_add_f32_dpp v38, v38, v38 row_half_mirror row_mask:0xf bank_mask:0xf bound_ctrl:1
	v_add_f32_e32 v0, v0, v1
	ds_write_b32 v50, v0 offset:3072
	v_add_f32_dpp v38, v38, v38 row_mirror row_mask:0xf bank_mask:0xf bound_ctrl:1
	v_pk_fma_f32 v[18:19], v[34:35], v[38:39], v[18:19] op_sel_hi:[1,0,1]
	v_pk_fma_f32 v[20:21], v[36:37], v[38:39], v[20:21] op_sel_hi:[1,0,1]
	ds_read_b128 v[96:99], v67 offset:23552
	ds_read_b32 v110, v70 offset:23808
	ds_read_b128 v[104:107], v67 offset:24320
	ds_read_b128 v[92:95], v67 offset:23040
	s_waitcnt lgkmcnt(7)
	v_pk_mul_f32 v[86:87], v[20:21], v[86:87]
	v_pk_mul_f32 v[80:81], v[108:109], v[80:81] op_sel_hi:[0,1]
	v_pk_fma_f32 v[84:85], v[18:19], v[84:85], v[86:87]
	v_pk_mul_f32 v[82:83], v[108:109], v[82:83] op_sel_hi:[0,1]
	v_add_f32_e32 v84, v84, v85
	v_pk_mul_f32 v[14:15], v[14:15], v[20:21]
	v_pk_fma_f32 v[76:77], v[18:19], v[76:77], v[80:81]
	v_add_f32_dpp v84, v84, v84 quad_perm:[1,0,3,2] row_mask:0xf bank_mask:0xf bound_ctrl:1
	ds_read_b128 v[26:29], v67 offset:25600
	v_pk_fma_f32 v[78:79], v[20:21], v[78:79], v[82:83]
	v_add_f32_dpp v84, v84, v84 quad_perm:[2,3,0,1] row_mask:0xf bank_mask:0xf bound_ctrl:1
	v_pk_fma_f32 v[12:13], v[12:13], v[18:19], v[14:15]
	ds_read_b128 v[4:7], v67 offset:24832
	v_add_f32_dpp v84, v84, v84 row_half_mirror row_mask:0xf bank_mask:0xf bound_ctrl:1
	v_add_f32_e32 v12, v12, v13
	ds_write_b32 v50, v12 offset:3328
	v_add_f32_dpp v84, v84, v84 row_mirror row_mask:0xf bank_mask:0xf bound_ctrl:1
	v_pk_fma_f32 v[76:77], v[88:89], v[84:85], v[76:77] op_sel_hi:[1,0,1]
	v_pk_fma_f32 v[78:79], v[90:91], v[84:85], v[78:79] op_sel_hi:[1,0,1]
	ds_read_b128 v[8:11], v67 offset:25088
	ds_read_b32 v64, v70 offset:25344
	ds_read_b128 v[22:25], v67 offset:25856
	ds_read_b128 v[0:3], v67 offset:24576
	s_waitcnt lgkmcnt(7)
	v_pk_mul_f32 v[102:103], v[78:79], v[102:103]
	v_pk_mul_f32 v[96:97], v[110:111], v[96:97] op_sel_hi:[0,1]
	v_pk_fma_f32 v[100:101], v[76:77], v[100:101], v[102:103]
	v_pk_mul_f32 v[98:99], v[110:111], v[98:99] op_sel_hi:[0,1]
	v_add_f32_e32 v100, v100, v101
	v_pk_mul_f32 v[74:75], v[74:75], v[78:79]
	v_pk_fma_f32 v[42:43], v[76:77], v[42:43], v[96:97]
	v_add_f32_dpp v100, v100, v100 quad_perm:[1,0,3,2] row_mask:0xf bank_mask:0xf bound_ctrl:1
	ds_read_b128 v[38:41], v67 offset:27136
	v_pk_fma_f32 v[44:45], v[78:79], v[44:45], v[98:99]
	v_add_f32_dpp v100, v100, v100 quad_perm:[2,3,0,1] row_mask:0xf bank_mask:0xf bound_ctrl:1
	v_pk_fma_f32 v[72:73], v[72:73], v[76:77], v[74:75]
	ds_read_b128 v[18:21], v67 offset:26368
	v_add_f32_dpp v100, v100, v100 row_half_mirror row_mask:0xf bank_mask:0xf bound_ctrl:1
	v_add_f32_e32 v72, v72, v73
	ds_write_b32 v50, v72 offset:3584
	v_add_f32_dpp v100, v100, v100 row_mirror row_mask:0xf bank_mask:0xf bound_ctrl:1
	v_pk_fma_f32 v[42:43], v[104:105], v[100:101], v[42:43] op_sel_hi:[1,0,1]
	v_pk_fma_f32 v[44:45], v[106:107], v[100:101], v[44:45] op_sel_hi:[1,0,1]
	ds_read_b128 v[30:33], v67 offset:26624
	ds_read_b32 v66, v70 offset:26880
	ds_read_b128 v[34:37], v67 offset:27392
	ds_read_b128 v[12:15], v67 offset:26112
	v_pk_mul_f32 v[94:95], v[94:95], v[44:45]
	s_nop 0
	v_pk_fma_f32 v[92:93], v[92:93], v[42:43], v[94:95]
	s_nop 0
	v_add_f32_e32 v92, v92, v93
	ds_write_b32 v50, v92 offset:3840
	s_waitcnt lgkmcnt(0)
	s_barrier
	s_waitcnt lgkmcnt(8)
	v_pk_mul_f32 v[28:29], v[44:45], v[28:29]
	v_pk_mul_f32 v[8:9], v[64:65], v[8:9] op_sel_hi:[0,1]
	v_pk_fma_f32 v[26:27], v[42:43], v[26:27], v[28:29]
	v_pk_mul_f32 v[10:11], v[64:65], v[10:11] op_sel_hi:[0,1]
	v_add_f32_e32 v26, v26, v27
	ds_read_b128 v[84:87], v67 offset:28672
	v_pk_fma_f32 v[4:5], v[42:43], v[4:5], v[8:9]
	v_add_f32_dpp v26, v26, v26 quad_perm:[1,0,3,2] row_mask:0xf bank_mask:0xf bound_ctrl:1
	ds_read_b128 v[76:79], v67 offset:27904
	v_pk_fma_f32 v[6:7], v[44:45], v[6:7], v[10:11]
	v_add_f32_dpp v26, v26, v26 quad_perm:[2,3,0,1] row_mask:0xf bank_mask:0xf bound_ctrl:1
	ds_read_b128 v[80:83], v67 offset:28160
	ds_read_b32 v108, v70 offset:28416
	v_add_f32_dpp v26, v26, v26 row_half_mirror row_mask:0xf bank_mask:0xf bound_ctrl:1
	ds_read_b128 v[88:91], v67 offset:28928
	ds_read_b128 v[72:75], v67 offset:27648
	v_add_f32_dpp v26, v26, v26 row_mirror row_mask:0xf bank_mask:0xf bound_ctrl:1
	v_pk_fma_f32 v[4:5], v[22:23], v[26:27], v[4:5] op_sel_hi:[1,0,1]
	v_pk_fma_f32 v[6:7], v[24:25], v[26:27], v[6:7] op_sel_hi:[1,0,1]
	s_nop 0
	s_waitcnt lgkmcnt(7)
; #define LAS __attribute__((address_space(3)))
; #define R4_ISSUE(cc, slot) do { const GAS float* g_ = gp + (size_t)(cc) * 2048; LAS float* l_ = ring + (slot) * 1536; _Pragma("unroll") for (int i_ = 0; i_ < 6; ++i_) \
;         __builtin_amdgcn_global_load_lds((const GAS unsigned*)(g_ + off[i_]), (LAS unsigned*)(l_ + i_ * 256), 16, 0, 0); } while (0)
; #define R4_LOAD(o, sb_) do { const LAS float* sb = (sb_); (o).r = *(const LAS f32x4*)(sb + cgp * 4); (o).w = *(const LAS f32x4*)(sb + 64 + cgp * 4); (o).k = *(const LAS f32x4*)(sb + 128 + cgp * 4); \
;         (o).a = *(const LAS f32x4*)(sb + 256 + cgp * 4); (o).b = *(const LAS f32x4*)(sb + 320 + cgp * 4); (o).vv = sb[192 + rq * 4 + rl]; asm volatile("" ::: "memory"); } while (0)
; __device__ __forceinline__ void rwkv_prompt_wave4(LAS float* ring, const GAS float* RW, int mbase, int h, int rq, GAS float* Sout, GAS float* YR, int lane) {
;     ...
;     for (int cc = 0; cc < 3; ++cc) R4_ISSUE(cc, cc);
;     float ykeep = 0.f;
;     R4Ops oA, oB, oC, oD;
;     asm volatile("s_waitcnt vmcnt(12)" ::: "memory");
;     R4_LOAD(oA, ring); R4_LOAD(oB, ring + 384);
;     for (int ci = 0; ci < NCH; ++ci) {
;         { const int cn = ci + 3; const int cl = cn < NCH ? cn : NCH - 1; R4_ISSUE(cl, cn % R4_NS); }
;         const LAS float* cb = ring + (ci % R4_NS) * 1536; const LAS float* nb = ring + ((ci + 1) % R4_NS) * 1536;
;         R4_LOAD(oC, cb + 768);  R4_STEP(oA, 0);
;         R4_LOAD(oD, cb + 1152); R4_STEP(oB, 1);
;         asm volatile("s_waitcnt vmcnt(12)" ::: "memory");
;         R4_LOAD(oA, nb);        R4_STEP(oC, 2);
;         R4_LOAD(oB, nb + 384);  R4_STEP(oD, 3);
;         if (cgp < 4) YR[(size_t)(mbase + ci * 4 + cgp) * 512 + h * 64 + rq * 4 + rl] = ykeep;
;     }
	v_pk_mul_f32 v[40:41], v[6:7], v[40:41]
	v_pk_mul_f32 v[30:31], v[66:67], v[30:31] op_sel_hi:[0,1]
	v_pk_fma_f32 v[38:39], v[4:5], v[38:39], v[40:41]
	v_pk_mul_f32 v[32:33], v[66:67], v[32:33] op_sel_hi:[0,1]
	v_add_f32_e32 v38, v38, v39
	v_pk_mul_f32 v[2:3], v[2:3], v[6:7]
	v_pk_fma_f32 v[18:19], v[4:5], v[18:19], v[30:31]
	v_add_f32_dpp v38, v38, v38 quad_perm:[1,0,3,2] row_mask:0xf bank_mask:0xf bound_ctrl:1
	ds_read_b128 v[100:103], v67 offset:30208
	v_pk_fma_f32 v[20:21], v[6:7], v[20:21], v[32:33]
	v_add_f32_dpp v38, v38, v38 quad_perm:[2,3,0,1] row_mask:0xf bank_mask:0xf bound_ctrl:1
	v_pk_fma_f32 v[0:1], v[0:1], v[4:5], v[2:3]
	ds_read_b128 v[42:45], v67 offset:29440
	v_add_f32_dpp v38, v38, v38 row_half_mirror row_mask:0xf bank_mask:0xf bound_ctrl:1
	v_add_f32_e32 v0, v0, v1
	ds_write_b32 v50, v0 offset:4096
	v_add_f32_dpp v38, v38, v38 row_mirror row_mask:0xf bank_mask:0xf bound_ctrl:1
	v_pk_fma_f32 v[18:19], v[34:35], v[38:39], v[18:19] op_sel_hi:[1,0,1]
	v_pk_fma_f32 v[20:21], v[36:37], v[38:39], v[20:21] op_sel_hi:[1,0,1]
	ds_read_b128 v[96:99], v67 offset:29696
	ds_read_b32 v110, v70 offset:29952
	ds_read_b128 v[104:107], v67 offset:30464
	ds_read_b128 v[92:95], v67 offset:29184
	s_waitcnt lgkmcnt(7)
	v_pk_mul_f32 v[86:87], v[20:21], v[86:87]
	v_pk_mul_f32 v[80:81], v[108:109], v[80:81] op_sel_hi:[0,1]
	v_pk_fma_f32 v[84:85], v[18:19], v[84:85], v[86:87]
	v_pk_mul_f32 v[82:83], v[108:109], v[82:83] op_sel_hi:[0,1]
	v_add_f32_e32 v84, v84, v85
	v_pk_mul_f32 v[14:15], v[14:15], v[20:21]
	v_pk_fma_f32 v[76:77], v[18:19], v[76:77], v[80:81]
	v_add_f32_dpp v84, v84, v84 quad_perm:[1,0,3,2] row_mask:0xf bank_mask:0xf bound_ctrl:1
	ds_read_b128 v[26:29], v67 offset:31744
	v_pk_fma_f32 v[78:79], v[20:21], v[78:79], v[82:83]
	v_add_f32_dpp v84, v84, v84 quad_perm:[2,3,0,1] row_mask:0xf bank_mask:0xf bound_ctrl:1
	v_pk_fma_f32 v[12:13], v[12:13], v[18:19], v[14:15]
	ds_read_b128 v[4:7], v67 offset:30976
	v_add_f32_dpp v84, v84, v84 row_half_mirror row_mask:0xf bank_mask:0xf bound_ctrl:1
	v_add_f32_e32 v12, v12, v13
	ds_write_b32 v50, v12 offset:4352
	v_add_f32_dpp v84, v84, v84 row_mirror row_mask:0xf bank_mask:0xf bound_ctrl:1
	v_pk_fma_f32 v[76:77], v[88:89], v[84:85], v[76:77] op_sel_hi:[1,0,1]
	v_pk_fma_f32 v[78:79], v[90:91], v[84:85], v[78:79] op_sel_hi:[1,0,1]
	ds_read_b128 v[8:11], v67 offset:31232
	ds_read_b32 v64, v70 offset:31488
	ds_read_b128 v[22:25], v67 offset:32000
	ds_read_b128 v[0:3], v67 offset:30720
	s_waitcnt lgkmcnt(7)
	v_pk_mul_f32 v[102:103], v[78:79], v[102:103]
	v_pk_mul_f32 v[96:97], v[110:111], v[96:97] op_sel_hi:[0,1]
	v_pk_fma_f32 v[100:101], v[76:77], v[100:101], v[102:103]
	v_pk_mul_f32 v[98:99], v[110:111], v[98:99] op_sel_hi:[0,1]
	v_add_f32_e32 v100, v100, v101
	v_pk_mul_f32 v[74:75], v[74:75], v[78:79]
	v_pk_fma_f32 v[42:43], v[76:77], v[42:43], v[96:97]
	v_add_f32_dpp v100, v100, v100 quad_perm:[1,0,3,2] row_mask:0xf bank_mask:0xf bound_ctrl:1
	ds_read_b128 v[38:41], v67 offset:33280
	v_pk_fma_f32 v[44:45], v[78:79], v[44:45], v[98:99]
	v_add_f32_dpp v100, v100, v100 quad_perm:[2,3,0,1] row_mask:0xf bank_mask:0xf bound_ctrl:1
	v_pk_fma_f32 v[72:73], v[72:73], v[76:77], v[74:75]
	ds_read_b128 v[18:21], v67 offset:32512
	v_add_f32_dpp v100, v100, v100 row_half_mirror row_mask:0xf bank_mask:0xf bound_ctrl:1
	v_add_f32_e32 v72, v72, v73
	ds_write_b32 v50, v72 offset:4608
	v_add_f32_dpp v100, v100, v100 row_mirror row_mask:0xf bank_mask:0xf bound_ctrl:1
	v_pk_fma_f32 v[42:43], v[104:105], v[100:101], v[42:43] op_sel_hi:[1,0,1]
	v_pk_fma_f32 v[44:45], v[106:107], v[100:101], v[44:45] op_sel_hi:[1,0,1]
	ds_read_b128 v[30:33], v67 offset:32768
	ds_read_b32 v66, v70 offset:33024
	ds_read_b128 v[34:37], v67 offset:33536
	ds_read_b128 v[12:15], v67 offset:32256
	v_pk_mul_f32 v[94:95], v[94:95], v[44:45]
	s_nop 0
	v_pk_fma_f32 v[92:93], v[92:93], v[42:43], v[94:95]
	s_nop 0
	v_add_f32_e32 v92, v92, v93
	ds_write_b32 v50, v92 offset:4864
	s_waitcnt lgkmcnt(8)
	v_pk_mul_f32 v[28:29], v[44:45], v[28:29]
	v_pk_mul_f32 v[8:9], v[64:65], v[8:9] op_sel_hi:[0,1]
	v_pk_fma_f32 v[26:27], v[42:43], v[26:27], v[28:29]
	v_pk_mul_f32 v[10:11], v[64:65], v[10:11] op_sel_hi:[0,1]
	v_add_f32_e32 v26, v26, v27
	ds_read_b128 v[84:87], v67 offset:34816
	v_pk_fma_f32 v[4:5], v[42:43], v[4:5], v[8:9]
	v_add_f32_dpp v26, v26, v26 quad_perm:[1,0,3,2] row_mask:0xf bank_mask:0xf bound_ctrl:1
	ds_read_b128 v[76:79], v67 offset:34048
	v_pk_fma_f32 v[6:7], v[44:45], v[6:7], v[10:11]
	v_add_f32_dpp v26, v26, v26 quad_perm:[2,3,0,1] row_mask:0xf bank_mask:0xf bound_ctrl:1
	ds_read_b128 v[80:83], v67 offset:34304
	ds_read_b32 v108, v70 offset:34560
	v_add_f32_dpp v26, v26, v26 row_half_mirror row_mask:0xf bank_mask:0xf bound_ctrl:1
	ds_read_b128 v[88:91], v67 offset:35072
	ds_read_b128 v[72:75], v67 offset:33792
	v_add_f32_dpp v26, v26, v26 row_mirror row_mask:0xf bank_mask:0xf bound_ctrl:1
	v_pk_fma_f32 v[4:5], v[22:23], v[26:27], v[4:5] op_sel_hi:[1,0,1]
	v_pk_fma_f32 v[6:7], v[24:25], v[26:27], v[6:7] op_sel_hi:[1,0,1]
	s_nop 0
	s_waitcnt lgkmcnt(7)
; #define LAS __attribute__((address_space(3)))
; #define R4_ISSUE(cc, slot) do { const GAS float* g_ = gp + (size_t)(cc) * 2048; LAS float* l_ = ring + (slot) * 1536; _Pragma("unroll") for (int i_ = 0; i_ < 6; ++i_) \
;         __builtin_amdgcn_global_load_lds((const GAS unsigned*)(g_ + off[i_]), (LAS unsigned*)(l_ + i_ * 256), 16, 0, 0); } while (0)
; #define R4_LOAD(o, sb_) do { const LAS float* sb = (sb_); (o).r = *(const LAS f32x4*)(sb + cgp * 4); (o).w = *(const LAS f32x4*)(sb + 64 + cgp * 4); (o).k = *(const LAS f32x4*)(sb + 128 + cgp * 4); \
;         (o).a = *(const LAS f32x4*)(sb + 256 + cgp * 4); (o).b = *(const LAS f32x4*)(sb + 320 + cgp * 4); (o).vv = sb[192 + rq * 4 + rl]; asm volatile("" ::: "memory"); } while (0)
; __device__ __forceinline__ void rwkv_prompt_wave4(LAS float* ring, const GAS float* RW, int mbase, int h, int rq, GAS float* Sout, GAS float* YR, int lane) {
;     ...
;     for (int cc = 0; cc < 3; ++cc) R4_ISSUE(cc, cc);
;     float ykeep = 0.f;
;     R4Ops oA, oB, oC, oD;
;     asm volatile("s_waitcnt vmcnt(12)" ::: "memory");
;     R4_LOAD(oA, ring); R4_LOAD(oB, ring + 384);
;     for (int ci = 0; ci < NCH; ++ci) {
;         { const int cn = ci + 3; const int cl = cn < NCH ? cn : NCH - 1; R4_ISSUE(cl, cn % R4_NS); }
;         const LAS float* cb = ring + (ci % R4_NS) * 1536; const LAS float* nb = ring + ((ci + 1) % R4_NS) * 1536;
;         R4_LOAD(oC, cb + 768);  R4_STEP(oA, 0);
;         R4_LOAD(oD, cb + 1152); R4_STEP(oB, 1);
;         asm volatile("s_waitcnt vmcnt(12)" ::: "memory");
;         R4_LOAD(oA, nb);        R4_STEP(oC, 2);
;         R4_LOAD(oB, nb + 384);  R4_STEP(oD, 3);
;         if (cgp < 4) YR[(size_t)(mbase + ci * 4 + cgp) * 512 + h * 64 + rq * 4 + rl] = ykeep;
;     }
	v_pk_mul_f32 v[40:41], v[6:7], v[40:41]
	v_pk_mul_f32 v[30:31], v[66:67], v[30:31] op_sel_hi:[0,1]
	v_pk_fma_f32 v[38:39], v[4:5], v[38:39], v[40:41]
	v_pk_mul_f32 v[32:33], v[66:67], v[32:33] op_sel_hi:[0,1]
	v_add_f32_e32 v38, v38, v39
	v_pk_mul_f32 v[2:3], v[2:3], v[6:7]
	v_pk_fma_f32 v[18:19], v[4:5], v[18:19], v[30:31]
	v_add_f32_dpp v38, v38, v38 quad_perm:[1,0,3,2] row_mask:0xf bank_mask:0xf bound_ctrl:1
	ds_read_b128 v[100:103], v67 offset:36352
	v_pk_fma_f32 v[20:21], v[6:7], v[20:21], v[32:33]
	v_add_f32_dpp v38, v38, v38 quad_perm:[2,3,0,1] row_mask:0xf bank_mask:0xf bound_ctrl:1
	v_pk_fma_f32 v[0:1], v[0:1], v[4:5], v[2:3]
	ds_read_b128 v[42:45], v67 offset:35584
	v_add_f32_dpp v38, v38, v38 row_half_mirror row_mask:0xf bank_mask:0xf bound_ctrl:1
	v_add_f32_e32 v0, v0, v1
	ds_write_b32 v50, v0 offset:5120
	v_add_f32_dpp v38, v38, v38 row_mirror row_mask:0xf bank_mask:0xf bound_ctrl:1
	v_pk_fma_f32 v[18:19], v[34:35], v[38:39], v[18:19] op_sel_hi:[1,0,1]
	v_pk_fma_f32 v[20:21], v[36:37], v[38:39], v[20:21] op_sel_hi:[1,0,1]
	ds_read_b128 v[96:99], v67 offset:35840
	ds_read_b32 v110, v70 offset:36096
	ds_read_b128 v[104:107], v67 offset:36608
	ds_read_b128 v[92:95], v67 offset:35328
	s_waitcnt lgkmcnt(7)
	v_pk_mul_f32 v[86:87], v[20:21], v[86:87]
	v_pk_mul_f32 v[80:81], v[108:109], v[80:81] op_sel_hi:[0,1]
	v_pk_fma_f32 v[84:85], v[18:19], v[84:85], v[86:87]
	v_pk_mul_f32 v[82:83], v[108:109], v[82:83] op_sel_hi:[0,1]
	v_add_f32_e32 v84, v84, v85
	v_pk_mul_f32 v[14:15], v[14:15], v[20:21]
	v_pk_fma_f32 v[76:77], v[18:19], v[76:77], v[80:81]
	v_add_f32_dpp v84, v84, v84 quad_perm:[1,0,3,2] row_mask:0xf bank_mask:0xf bound_ctrl:1
	ds_read_b128 v[26:29], v67 offset:37888
	v_pk_fma_f32 v[78:79], v[20:21], v[78:79], v[82:83]
	v_add_f32_dpp v84, v84, v84 quad_perm:[2,3,0,1] row_mask:0xf bank_mask:0xf bound_ctrl:1
	v_pk_fma_f32 v[12:13], v[12:13], v[18:19], v[14:15]
	ds_read_b128 v[4:7], v67 offset:37120
	v_add_f32_dpp v84, v84, v84 row_half_mirror row_mask:0xf bank_mask:0xf bound_ctrl:1
	v_add_f32_e32 v12, v12, v13
	ds_write_b32 v50, v12 offset:5376
	v_add_f32_dpp v84, v84, v84 row_mirror row_mask:0xf bank_mask:0xf bound_ctrl:1
	v_pk_fma_f32 v[76:77], v[88:89], v[84:85], v[76:77] op_sel_hi:[1,0,1]
	v_pk_fma_f32 v[78:79], v[90:91], v[84:85], v[78:79] op_sel_hi:[1,0,1]
	ds_read_b128 v[8:11], v67 offset:37376
	ds_read_b32 v64, v70 offset:37632
	ds_read_b128 v[22:25], v67 offset:38144
	ds_read_b128 v[0:3], v67 offset:36864
	s_waitcnt lgkmcnt(7)
	v_pk_mul_f32 v[102:103], v[78:79], v[102:103]
	v_pk_mul_f32 v[96:97], v[110:111], v[96:97] op_sel_hi:[0,1]
	v_pk_fma_f32 v[100:101], v[76:77], v[100:101], v[102:103]
	v_pk_mul_f32 v[98:99], v[110:111], v[98:99] op_sel_hi:[0,1]
	v_add_f32_e32 v100, v100, v101
	v_pk_mul_f32 v[74:75], v[74:75], v[78:79]
	v_pk_fma_f32 v[42:43], v[76:77], v[42:43], v[96:97]
	v_add_f32_dpp v100, v100, v100 quad_perm:[1,0,3,2] row_mask:0xf bank_mask:0xf bound_ctrl:1
	ds_read_b128 v[38:41], v67 offset:39424
	v_pk_fma_f32 v[44:45], v[78:79], v[44:45], v[98:99]
	v_add_f32_dpp v100, v100, v100 quad_perm:[2,3,0,1] row_mask:0xf bank_mask:0xf bound_ctrl:1
	v_pk_fma_f32 v[72:73], v[72:73], v[76:77], v[74:75]
	ds_read_b128 v[18:21], v67 offset:38656
	v_add_f32_dpp v100, v100, v100 row_half_mirror row_mask:0xf bank_mask:0xf bound_ctrl:1
	v_add_f32_e32 v72, v72, v73
	ds_write_b32 v50, v72 offset:5632
	v_add_f32_dpp v100, v100, v100 row_mirror row_mask:0xf bank_mask:0xf bound_ctrl:1
	v_pk_fma_f32 v[42:43], v[104:105], v[100:101], v[42:43] op_sel_hi:[1,0,1]
	v_pk_fma_f32 v[44:45], v[106:107], v[100:101], v[44:45] op_sel_hi:[1,0,1]
	ds_read_b128 v[30:33], v67 offset:38912
	ds_read_b32 v66, v70 offset:39168
	ds_read_b128 v[34:37], v67 offset:39680
	ds_read_b128 v[12:15], v67 offset:38400
	v_pk_mul_f32 v[94:95], v[94:95], v[44:45]
	s_nop 0
	v_pk_fma_f32 v[92:93], v[92:93], v[42:43], v[94:95]
	s_nop 0
	v_add_f32_e32 v92, v92, v93
	ds_write_b32 v50, v92 offset:5888
	s_waitcnt lgkmcnt(8)
	v_pk_mul_f32 v[28:29], v[44:45], v[28:29]
	v_pk_mul_f32 v[8:9], v[64:65], v[8:9] op_sel_hi:[0,1]
	v_pk_fma_f32 v[26:27], v[42:43], v[26:27], v[28:29]
	v_pk_mul_f32 v[10:11], v[64:65], v[10:11] op_sel_hi:[0,1]
	v_add_f32_e32 v26, v26, v27
	ds_read_b128 v[84:87], v67 offset:40960
	v_pk_fma_f32 v[4:5], v[42:43], v[4:5], v[8:9]
	v_add_f32_dpp v26, v26, v26 quad_perm:[1,0,3,2] row_mask:0xf bank_mask:0xf bound_ctrl:1
	ds_read_b128 v[76:79], v67 offset:40192
	v_pk_fma_f32 v[6:7], v[44:45], v[6:7], v[10:11]
	v_add_f32_dpp v26, v26, v26 quad_perm:[2,3,0,1] row_mask:0xf bank_mask:0xf bound_ctrl:1
	ds_read_b128 v[80:83], v67 offset:40448
	ds_read_b32 v108, v70 offset:40704
	v_add_f32_dpp v26, v26, v26 row_half_mirror row_mask:0xf bank_mask:0xf bound_ctrl:1
	ds_read_b128 v[88:91], v67 offset:41216
	ds_read_b128 v[72:75], v67 offset:39936
	v_add_f32_dpp v26, v26, v26 row_mirror row_mask:0xf bank_mask:0xf bound_ctrl:1
	v_pk_fma_f32 v[4:5], v[22:23], v[26:27], v[4:5] op_sel_hi:[1,0,1]
	v_pk_fma_f32 v[6:7], v[24:25], v[26:27], v[6:7] op_sel_hi:[1,0,1]
	s_nop 0
	s_waitcnt lgkmcnt(7)
; #define LAS __attribute__((address_space(3)))
; #define R4_ISSUE(cc, slot) do { const GAS float* g_ = gp + (size_t)(cc) * 2048; LAS float* l_ = ring + (slot) * 1536; _Pragma("unroll") for (int i_ = 0; i_ < 6; ++i_) \
;         __builtin_amdgcn_global_load_lds((const GAS unsigned*)(g_ + off[i_]), (LAS unsigned*)(l_ + i_ * 256), 16, 0, 0); } while (0)
; #define R4_LOAD(o, sb_) do { const LAS float* sb = (sb_); (o).r = *(const LAS f32x4*)(sb + cgp * 4); (o).w = *(const LAS f32x4*)(sb + 64 + cgp * 4); (o).k = *(const LAS f32x4*)(sb + 128 + cgp * 4); \
;         (o).a = *(const LAS f32x4*)(sb + 256 + cgp * 4); (o).b = *(const LAS f32x4*)(sb + 320 + cgp * 4); (o).vv = sb[192 + rq * 4 + rl]; asm volatile("" ::: "memory"); } while (0)
; __device__ __forceinline__ void rwkv_prompt_wave4(LAS float* ring, const GAS float* RW, int mbase, int h, int rq, GAS float* Sout, GAS float* YR, int lane) {
;     ...
;     for (int cc = 0; cc < 3; ++cc) R4_ISSUE(cc, cc);
;     float ykeep = 0.f;
;     R4Ops oA, oB, oC, oD;
;     asm volatile("s_waitcnt vmcnt(12)" ::: "memory");
;     R4_LOAD(oA, ring); R4_LOAD(oB, ring + 384);
;     for (int ci = 0; ci < NCH; ++ci) {
;         { const int cn = ci + 3; const int cl = cn < NCH ? cn : NCH - 1; R4_ISSUE(cl, cn % R4_NS); }
;         const LAS float* cb = ring + (ci % R4_NS) * 1536; const LAS float* nb = ring + ((ci + 1) % R4_NS) * 1536;
;         R4_LOAD(oC, cb + 768);  R4_STEP(oA, 0);
;         R4_LOAD(oD, cb + 1152); R4_STEP(oB, 1);
;         asm volatile("s_waitcnt vmcnt(12)" ::: "memory");
;         R4_LOAD(oA, nb);        R4_STEP(oC, 2);
;         R4_LOAD(oB, nb + 384);  R4_STEP(oD, 3);
;         if (cgp < 4) YR[(size_t)(mbase + ci * 4 + cgp) * 512 + h * 64 + rq * 4 + rl] = ykeep;
;     }
	v_pk_mul_f32 v[40:41], v[6:7], v[40:41]
	v_pk_mul_f32 v[30:31], v[66:67], v[30:31] op_sel_hi:[0,1]
	v_pk_fma_f32 v[38:39], v[4:5], v[38:39], v[40:41]
	v_pk_mul_f32 v[32:33], v[66:67], v[32:33] op_sel_hi:[0,1]
	v_add_f32_e32 v38, v38, v39
	v_pk_mul_f32 v[2:3], v[2:3], v[6:7]
	v_pk_fma_f32 v[18:19], v[4:5], v[18:19], v[30:31]
	v_add_f32_dpp v38, v38, v38 quad_perm:[1,0,3,2] row_mask:0xf bank_mask:0xf bound_ctrl:1
	ds_read_b128 v[100:103], v67 offset:42496
	v_pk_fma_f32 v[20:21], v[6:7], v[20:21], v[32:33]
	v_add_f32_dpp v38, v38, v38 quad_perm:[2,3,0,1] row_mask:0xf bank_mask:0xf bound_ctrl:1
	v_pk_fma_f32 v[0:1], v[0:1], v[4:5], v[2:3]
	ds_read_b128 v[42:45], v67 offset:41728
	v_add_f32_dpp v38, v38, v38 row_half_mirror row_mask:0xf bank_mask:0xf bound_ctrl:1
	v_add_f32_e32 v0, v0, v1
	ds_write_b32 v50, v0 offset:6144
	v_add_f32_dpp v38, v38, v38 row_mirror row_mask:0xf bank_mask:0xf bound_ctrl:1
	v_pk_fma_f32 v[18:19], v[34:35], v[38:39], v[18:19] op_sel_hi:[1,0,1]
	v_pk_fma_f32 v[20:21], v[36:37], v[38:39], v[20:21] op_sel_hi:[1,0,1]
	ds_read_b128 v[96:99], v67 offset:41984
	ds_read_b32 v110, v70 offset:42240
	ds_read_b128 v[104:107], v67 offset:42752
	ds_read_b128 v[92:95], v67 offset:41472
	s_waitcnt lgkmcnt(7)
	v_pk_mul_f32 v[86:87], v[20:21], v[86:87]
	v_pk_mul_f32 v[80:81], v[108:109], v[80:81] op_sel_hi:[0,1]
	v_pk_fma_f32 v[84:85], v[18:19], v[84:85], v[86:87]
	v_pk_mul_f32 v[82:83], v[108:109], v[82:83] op_sel_hi:[0,1]
	v_add_f32_e32 v84, v84, v85
	v_pk_mul_f32 v[14:15], v[14:15], v[20:21]
	v_pk_fma_f32 v[76:77], v[18:19], v[76:77], v[80:81]
	v_add_f32_dpp v84, v84, v84 quad_perm:[1,0,3,2] row_mask:0xf bank_mask:0xf bound_ctrl:1
	ds_read_b128 v[26:29], v67 offset:44032
	v_pk_fma_f32 v[78:79], v[20:21], v[78:79], v[82:83]
	v_add_f32_dpp v84, v84, v84 quad_perm:[2,3,0,1] row_mask:0xf bank_mask:0xf bound_ctrl:1
	v_pk_fma_f32 v[12:13], v[12:13], v[18:19], v[14:15]
	ds_read_b128 v[4:7], v67 offset:43264
	v_add_f32_dpp v84, v84, v84 row_half_mirror row_mask:0xf bank_mask:0xf bound_ctrl:1
	v_add_f32_e32 v12, v12, v13
	ds_write_b32 v50, v12 offset:6400
	v_add_f32_dpp v84, v84, v84 row_mirror row_mask:0xf bank_mask:0xf bound_ctrl:1
	v_pk_fma_f32 v[76:77], v[88:89], v[84:85], v[76:77] op_sel_hi:[1,0,1]
	v_pk_fma_f32 v[78:79], v[90:91], v[84:85], v[78:79] op_sel_hi:[1,0,1]
	ds_read_b128 v[8:11], v67 offset:43520
	ds_read_b32 v64, v70 offset:43776
	ds_read_b128 v[22:25], v67 offset:44288
	ds_read_b128 v[0:3], v67 offset:43008
	s_waitcnt lgkmcnt(7)
	v_pk_mul_f32 v[102:103], v[78:79], v[102:103]
	v_pk_mul_f32 v[96:97], v[110:111], v[96:97] op_sel_hi:[0,1]
	v_pk_fma_f32 v[100:101], v[76:77], v[100:101], v[102:103]
	v_pk_mul_f32 v[98:99], v[110:111], v[98:99] op_sel_hi:[0,1]
	v_add_f32_e32 v100, v100, v101
	v_pk_mul_f32 v[74:75], v[74:75], v[78:79]
	v_pk_fma_f32 v[42:43], v[76:77], v[42:43], v[96:97]
	v_add_f32_dpp v100, v100, v100 quad_perm:[1,0,3,2] row_mask:0xf bank_mask:0xf bound_ctrl:1
	ds_read_b128 v[38:41], v67 offset:45568
	v_pk_fma_f32 v[44:45], v[78:79], v[44:45], v[98:99]
	v_add_f32_dpp v100, v100, v100 quad_perm:[2,3,0,1] row_mask:0xf bank_mask:0xf bound_ctrl:1
	v_pk_fma_f32 v[72:73], v[72:73], v[76:77], v[74:75]
	ds_read_b128 v[18:21], v67 offset:44800
	v_add_f32_dpp v100, v100, v100 row_half_mirror row_mask:0xf bank_mask:0xf bound_ctrl:1
	v_add_f32_e32 v72, v72, v73
	ds_write_b32 v50, v72 offset:6656
	v_add_f32_dpp v100, v100, v100 row_mirror row_mask:0xf bank_mask:0xf bound_ctrl:1
	v_pk_fma_f32 v[42:43], v[104:105], v[100:101], v[42:43] op_sel_hi:[1,0,1]
	v_pk_fma_f32 v[44:45], v[106:107], v[100:101], v[44:45] op_sel_hi:[1,0,1]
	ds_read_b128 v[30:33], v67 offset:45056
	ds_read_b32 v66, v70 offset:45312
	ds_read_b128 v[34:37], v67 offset:45824
	ds_read_b128 v[12:15], v67 offset:44544
	v_pk_mul_f32 v[94:95], v[94:95], v[44:45]
	s_nop 0
	v_pk_fma_f32 v[92:93], v[92:93], v[42:43], v[94:95]
	s_nop 0
	v_add_f32_e32 v92, v92, v93
	ds_write_b32 v50, v92 offset:6912
	s_waitcnt lgkmcnt(8)
	v_pk_mul_f32 v[28:29], v[44:45], v[28:29]
	v_pk_mul_f32 v[8:9], v[64:65], v[8:9] op_sel_hi:[0,1]
	v_pk_fma_f32 v[26:27], v[42:43], v[26:27], v[28:29]
	v_pk_mul_f32 v[10:11], v[64:65], v[10:11] op_sel_hi:[0,1]
	v_add_f32_e32 v26, v26, v27
	ds_read_b128 v[84:87], v67 offset:47104
	v_pk_fma_f32 v[4:5], v[42:43], v[4:5], v[8:9]
	v_add_f32_dpp v26, v26, v26 quad_perm:[1,0,3,2] row_mask:0xf bank_mask:0xf bound_ctrl:1
	ds_read_b128 v[76:79], v67 offset:46336
	v_pk_fma_f32 v[6:7], v[44:45], v[6:7], v[10:11]
	v_add_f32_dpp v26, v26, v26 quad_perm:[2,3,0,1] row_mask:0xf bank_mask:0xf bound_ctrl:1
	ds_read_b128 v[80:83], v67 offset:46592
	ds_read_b32 v108, v70 offset:46848
	v_add_f32_dpp v26, v26, v26 row_half_mirror row_mask:0xf bank_mask:0xf bound_ctrl:1
	ds_read_b128 v[88:91], v67 offset:47360
	ds_read_b128 v[72:75], v67 offset:46080
	v_add_f32_dpp v26, v26, v26 row_mirror row_mask:0xf bank_mask:0xf bound_ctrl:1
	v_pk_fma_f32 v[4:5], v[22:23], v[26:27], v[4:5] op_sel_hi:[1,0,1]
	v_pk_fma_f32 v[6:7], v[24:25], v[26:27], v[6:7] op_sel_hi:[1,0,1]
	s_nop 0
	s_waitcnt lgkmcnt(7)
; #define LAS __attribute__((address_space(3)))
; #define R4_ISSUE(cc, slot) do { const GAS float* g_ = gp + (size_t)(cc) * 2048; LAS float* l_ = ring + (slot) * 1536; _Pragma("unroll") for (int i_ = 0; i_ < 6; ++i_) \
;         __builtin_amdgcn_global_load_lds((const GAS unsigned*)(g_ + off[i_]), (LAS unsigned*)(l_ + i_ * 256), 16, 0, 0); } while (0)
; #define R4_LOAD(o, sb_) do { const LAS float* sb = (sb_); (o).r = *(const LAS f32x4*)(sb + cgp * 4); (o).w = *(const LAS f32x4*)(sb + 64 + cgp * 4); (o).k = *(const LAS f32x4*)(sb + 128 + cgp * 4); \
;         (o).a = *(const LAS f32x4*)(sb + 256 + cgp * 4); (o).b = *(const LAS f32x4*)(sb + 320 + cgp * 4); (o).vv = sb[192 + rq * 4 + rl]; asm volatile("" ::: "memory"); } while (0)
; __device__ __forceinline__ void rwkv_prompt_wave4(LAS float* ring, const GAS float* RW, int mbase, int h, int rq, GAS float* Sout, GAS float* YR, int lane) {
;     ...
;     for (int cc = 0; cc < 3; ++cc) R4_ISSUE(cc, cc);
;     float ykeep = 0.f;
;     R4Ops oA, oB, oC, oD;
;     asm volatile("s_waitcnt vmcnt(12)" ::: "memory");
;     R4_LOAD(oA, ring); R4_LOAD(oB, ring + 384);
;     for (int ci = 0; ci < NCH; ++ci) {
;         { const int cn = ci + 3; const int cl = cn < NCH ? cn : NCH - 1; R4_ISSUE(cl, cn % R4_NS); }
;         const LAS float* cb = ring + (ci % R4_NS) * 1536; const LAS float* nb = ring + ((ci + 1) % R4_NS) * 1536;
;         R4_LOAD(oC, cb + 768);  R4_STEP(oA, 0);
;         R4_LOAD(oD, cb + 1152); R4_STEP(oB, 1);
;         asm volatile("s_waitcnt vmcnt(12)" ::: "memory");
;         R4_LOAD(oA, nb);        R4_STEP(oC, 2);
;         R4_LOAD(oB, nb + 384);  R4_STEP(oD, 3);
;         if (cgp < 4) YR[(size_t)(mbase + ci * 4 + cgp) * 512 + h * 64 + rq * 4 + rl] = ykeep;
;     }
	v_pk_mul_f32 v[40:41], v[6:7], v[40:41]
	v_pk_mul_f32 v[30:31], v[66:67], v[30:31] op_sel_hi:[0,1]
	v_pk_fma_f32 v[38:39], v[4:5], v[38:39], v[40:41]
	v_pk_mul_f32 v[32:33], v[66:67], v[32:33] op_sel_hi:[0,1]
	v_add_f32_e32 v38, v38, v39
	v_pk_mul_f32 v[2:3], v[2:3], v[6:7]
	v_pk_fma_f32 v[18:19], v[4:5], v[18:19], v[30:31]
	v_add_f32_dpp v38, v38, v38 quad_perm:[1,0,3,2] row_mask:0xf bank_mask:0xf bound_ctrl:1
	ds_read_b128 v[100:103], v67 offset:48640
	v_pk_fma_f32 v[20:21], v[6:7], v[20:21], v[32:33]
	v_add_f32_dpp v38, v38, v38 quad_perm:[2,3,0,1] row_mask:0xf bank_mask:0xf bound_ctrl:1
	v_pk_fma_f32 v[0:1], v[0:1], v[4:5], v[2:3]
	ds_read_b128 v[42:45], v67 offset:47872
	v_add_f32_dpp v38, v38, v38 row_half_mirror row_mask:0xf bank_mask:0xf bound_ctrl:1
	v_add_f32_e32 v0, v0, v1
	ds_write_b32 v50, v0 offset:7168
	v_add_f32_dpp v38, v38, v38 row_mirror row_mask:0xf bank_mask:0xf bound_ctrl:1
	v_pk_fma_f32 v[18:19], v[34:35], v[38:39], v[18:19] op_sel_hi:[1,0,1]
	v_pk_fma_f32 v[20:21], v[36:37], v[38:39], v[20:21] op_sel_hi:[1,0,1]
	ds_read_b128 v[96:99], v67 offset:48128
	ds_read_b32 v110, v70 offset:48384
	ds_read_b128 v[104:107], v67 offset:48896
	ds_read_b128 v[92:95], v67 offset:47616
	s_waitcnt lgkmcnt(7)
	v_pk_mul_f32 v[86:87], v[20:21], v[86:87]
	v_pk_mul_f32 v[80:81], v[108:109], v[80:81] op_sel_hi:[0,1]
	v_pk_fma_f32 v[84:85], v[18:19], v[84:85], v[86:87]
	v_pk_mul_f32 v[82:83], v[108:109], v[82:83] op_sel_hi:[0,1]
	v_add_f32_e32 v84, v84, v85
	v_pk_mul_f32 v[14:15], v[14:15], v[20:21]
	v_pk_fma_f32 v[76:77], v[18:19], v[76:77], v[80:81]
	v_add_f32_dpp v84, v84, v84 quad_perm:[1,0,3,2] row_mask:0xf bank_mask:0xf bound_ctrl:1
	ds_read_b128 v[26:29], v46 offset:1024
	v_pk_fma_f32 v[78:79], v[20:21], v[78:79], v[82:83]
	v_add_f32_dpp v84, v84, v84 quad_perm:[2,3,0,1] row_mask:0xf bank_mask:0xf bound_ctrl:1
	v_pk_fma_f32 v[12:13], v[12:13], v[18:19], v[14:15]
	ds_read_b128 v[4:7], v46 offset:256
	v_add_f32_dpp v84, v84, v84 row_half_mirror row_mask:0xf bank_mask:0xf bound_ctrl:1
	v_add_f32_e32 v12, v12, v13
	ds_write_b32 v50, v12 offset:7424
	v_add_f32_dpp v84, v84, v84 row_mirror row_mask:0xf bank_mask:0xf bound_ctrl:1
	v_pk_fma_f32 v[76:77], v[88:89], v[84:85], v[76:77] op_sel_hi:[1,0,1]
	v_pk_fma_f32 v[78:79], v[90:91], v[84:85], v[78:79] op_sel_hi:[1,0,1]
	ds_read_b128 v[8:11], v46 offset:512
	ds_read_b32 v64, v47 offset:768
	ds_read_b128 v[22:25], v46 offset:1280
	ds_read_b128 v[0:3], v46 offset:0
	s_waitcnt lgkmcnt(7)
	v_pk_mul_f32 v[102:103], v[78:79], v[102:103]
	v_pk_mul_f32 v[96:97], v[110:111], v[96:97] op_sel_hi:[0,1]
	v_pk_fma_f32 v[100:101], v[76:77], v[100:101], v[102:103]
	v_pk_mul_f32 v[98:99], v[110:111], v[98:99] op_sel_hi:[0,1]
	v_add_f32_e32 v100, v100, v101
	v_pk_mul_f32 v[74:75], v[74:75], v[78:79]
	v_pk_fma_f32 v[42:43], v[76:77], v[42:43], v[96:97]
	v_add_f32_dpp v100, v100, v100 quad_perm:[1,0,3,2] row_mask:0xf bank_mask:0xf bound_ctrl:1
	ds_read_b128 v[38:41], v46 offset:2560
	v_pk_fma_f32 v[44:45], v[78:79], v[44:45], v[98:99]
	v_add_f32_dpp v100, v100, v100 quad_perm:[2,3,0,1] row_mask:0xf bank_mask:0xf bound_ctrl:1
	v_pk_fma_f32 v[72:73], v[72:73], v[76:77], v[74:75]
	ds_read_b128 v[18:21], v46 offset:1792
	v_add_f32_dpp v100, v100, v100 row_half_mirror row_mask:0xf bank_mask:0xf bound_ctrl:1
	v_add_f32_e32 v72, v72, v73
	ds_write_b32 v50, v72 offset:7680
	v_add_f32_dpp v100, v100, v100 row_mirror row_mask:0xf bank_mask:0xf bound_ctrl:1
	v_pk_fma_f32 v[42:43], v[104:105], v[100:101], v[42:43] op_sel_hi:[1,0,1]
	v_pk_fma_f32 v[44:45], v[106:107], v[100:101], v[44:45] op_sel_hi:[1,0,1]
	ds_read_b128 v[30:33], v46 offset:2048
	ds_read_b32 v66, v47 offset:2304
	ds_read_b128 v[34:37], v46 offset:2816
	ds_read_b128 v[12:15], v46 offset:1536
	v_pk_mul_f32 v[94:95], v[94:95], v[44:45]
	s_nop 0
	v_pk_fma_f32 v[92:93], v[92:93], v[42:43], v[94:95]
	s_nop 0
	v_add_f32_e32 v92, v92, v93
	ds_write_b32 v50, v92 offset:7936
	s_waitcnt lgkmcnt(0)
	s_barrier
	s_waitcnt lgkmcnt(8)
	v_pk_mul_f32 v[28:29], v[44:45], v[28:29]
	v_pk_mul_f32 v[8:9], v[64:65], v[8:9] op_sel_hi:[0,1]
	v_pk_fma_f32 v[26:27], v[42:43], v[26:27], v[28:29]
	v_pk_mul_f32 v[10:11], v[64:65], v[10:11] op_sel_hi:[0,1]
	v_add_f32_e32 v26, v26, v27
	ds_read_b128 v[84:87], v46 offset:4096
	v_pk_fma_f32 v[4:5], v[42:43], v[4:5], v[8:9]
	v_add_f32_dpp v26, v26, v26 quad_perm:[1,0,3,2] row_mask:0xf bank_mask:0xf bound_ctrl:1
	ds_read_b128 v[76:79], v46 offset:3328
	v_pk_fma_f32 v[6:7], v[44:45], v[6:7], v[10:11]
	v_add_f32_dpp v26, v26, v26 quad_perm:[2,3,0,1] row_mask:0xf bank_mask:0xf bound_ctrl:1
	ds_read_b128 v[80:83], v46 offset:3584
	ds_read_b32 v108, v47 offset:3840
	v_add_f32_dpp v26, v26, v26 row_half_mirror row_mask:0xf bank_mask:0xf bound_ctrl:1
	ds_read_b128 v[88:91], v46 offset:4352
	ds_read_b128 v[72:75], v46 offset:3072
	v_add_f32_dpp v26, v26, v26 row_mirror row_mask:0xf bank_mask:0xf bound_ctrl:1
	v_pk_fma_f32 v[4:5], v[22:23], v[26:27], v[4:5] op_sel_hi:[1,0,1]
	v_pk_fma_f32 v[6:7], v[24:25], v[26:27], v[6:7] op_sel_hi:[1,0,1]
	s_nop 0
	s_waitcnt lgkmcnt(7)
; #define LAS __attribute__((address_space(3)))
; #define R4_ISSUE(cc, slot) do { const GAS float* g_ = gp + (size_t)(cc) * 2048; LAS float* l_ = ring + (slot) * 1536; _Pragma("unroll") for (int i_ = 0; i_ < 6; ++i_) \
;         __builtin_amdgcn_global_load_lds((const GAS unsigned*)(g_ + off[i_]), (LAS unsigned*)(l_ + i_ * 256), 16, 0, 0); } while (0)
; #define R4_LOAD(o, sb_) do { const LAS float* sb = (sb_); (o).r = *(const LAS f32x4*)(sb + cgp * 4); (o).w = *(const LAS f32x4*)(sb + 64 + cgp * 4); (o).k = *(const LAS f32x4*)(sb + 128 + cgp * 4); \
;         (o).a = *(const LAS f32x4*)(sb + 256 + cgp * 4); (o).b = *(const LAS f32x4*)(sb + 320 + cgp * 4); (o).vv = sb[192 + rq * 4 + rl]; asm volatile("" ::: "memory"); } while (0)
; __device__ __forceinline__ void rwkv_prompt_wave4(LAS float* ring, const GAS float* RW, int mbase, int h, int rq, GAS float* Sout, GAS float* YR, int lane) {
;     ...
;     for (int cc = 0; cc < 3; ++cc) R4_ISSUE(cc, cc);
;     float ykeep = 0.f;
;     R4Ops oA, oB, oC, oD;
;     asm volatile("s_waitcnt vmcnt(12)" ::: "memory");
;     R4_LOAD(oA, ring); R4_LOAD(oB, ring + 384);
;     for (int ci = 0; ci < NCH; ++ci) {
;         { const int cn = ci + 3; const int cl = cn < NCH ? cn : NCH - 1; R4_ISSUE(cl, cn % R4_NS); }
;         const LAS float* cb = ring + (ci % R4_NS) * 1536; const LAS float* nb = ring + ((ci + 1) % R4_NS) * 1536;
;         R4_LOAD(oC, cb + 768);  R4_STEP(oA, 0);
;         R4_LOAD(oD, cb + 1152); R4_STEP(oB, 1);
;         asm volatile("s_waitcnt vmcnt(12)" ::: "memory");
;         R4_LOAD(oA, nb);        R4_STEP(oC, 2);
;         R4_LOAD(oB, nb + 384);  R4_STEP(oD, 3);
;         if (cgp < 4) YR[(size_t)(mbase + ci * 4 + cgp) * 512 + h * 64 + rq * 4 + rl] = ykeep;
;     }
	v_pk_mul_f32 v[40:41], v[6:7], v[40:41]
	v_pk_mul_f32 v[30:31], v[66:67], v[30:31] op_sel_hi:[0,1]
	v_pk_fma_f32 v[38:39], v[4:5], v[38:39], v[40:41]
	v_pk_mul_f32 v[32:33], v[66:67], v[32:33] op_sel_hi:[0,1]
	v_add_f32_e32 v38, v38, v39
	v_pk_mul_f32 v[2:3], v[2:3], v[6:7]
	v_pk_fma_f32 v[18:19], v[4:5], v[18:19], v[30:31]
	v_add_f32_dpp v38, v38, v38 quad_perm:[1,0,3,2] row_mask:0xf bank_mask:0xf bound_ctrl:1
	ds_read_b128 v[100:103], v46 offset:5632
	v_pk_fma_f32 v[20:21], v[6:7], v[20:21], v[32:33]
	v_add_f32_dpp v38, v38, v38 quad_perm:[2,3,0,1] row_mask:0xf bank_mask:0xf bound_ctrl:1
	v_pk_fma_f32 v[0:1], v[0:1], v[4:5], v[2:3]
	ds_read_b128 v[42:45], v46 offset:4864
	v_add_f32_dpp v38, v38, v38 row_half_mirror row_mask:0xf bank_mask:0xf bound_ctrl:1
	v_add_f32_e32 v0, v0, v1
	ds_write_b32 v50, v0 offset:0
	v_add_f32_dpp v38, v38, v38 row_mirror row_mask:0xf bank_mask:0xf bound_ctrl:1
	v_pk_fma_f32 v[18:19], v[34:35], v[38:39], v[18:19] op_sel_hi:[1,0,1]
	v_pk_fma_f32 v[20:21], v[36:37], v[38:39], v[20:21] op_sel_hi:[1,0,1]
	ds_read_b128 v[96:99], v46 offset:5120
	ds_read_b32 v110, v47 offset:5376
	ds_read_b128 v[104:107], v46 offset:5888
	ds_read_b128 v[92:95], v46 offset:4608
	s_waitcnt lgkmcnt(7)
	v_pk_mul_f32 v[86:87], v[20:21], v[86:87]
	v_pk_mul_f32 v[80:81], v[108:109], v[80:81] op_sel_hi:[0,1]
	v_pk_fma_f32 v[84:85], v[18:19], v[84:85], v[86:87]
	v_pk_mul_f32 v[82:83], v[108:109], v[82:83] op_sel_hi:[0,1]
	v_add_f32_e32 v84, v84, v85
	v_pk_mul_f32 v[14:15], v[14:15], v[20:21]
	v_pk_fma_f32 v[76:77], v[18:19], v[76:77], v[80:81]
	v_add_f32_dpp v84, v84, v84 quad_perm:[1,0,3,2] row_mask:0xf bank_mask:0xf bound_ctrl:1
	ds_read_b128 v[26:29], v46 offset:7168
	v_pk_fma_f32 v[78:79], v[20:21], v[78:79], v[82:83]
	v_add_f32_dpp v84, v84, v84 quad_perm:[2,3,0,1] row_mask:0xf bank_mask:0xf bound_ctrl:1
	v_pk_fma_f32 v[12:13], v[12:13], v[18:19], v[14:15]
	ds_read_b128 v[4:7], v46 offset:6400
	v_add_f32_dpp v84, v84, v84 row_half_mirror row_mask:0xf bank_mask:0xf bound_ctrl:1
	v_add_f32_e32 v12, v12, v13
	ds_write_b32 v50, v12 offset:256
	v_add_f32_dpp v84, v84, v84 row_mirror row_mask:0xf bank_mask:0xf bound_ctrl:1
	v_pk_fma_f32 v[76:77], v[88:89], v[84:85], v[76:77] op_sel_hi:[1,0,1]
	v_pk_fma_f32 v[78:79], v[90:91], v[84:85], v[78:79] op_sel_hi:[1,0,1]
	ds_read_b128 v[8:11], v46 offset:6656
	ds_read_b32 v64, v47 offset:6912
	ds_read_b128 v[22:25], v46 offset:7424
	ds_read_b128 v[0:3], v46 offset:6144
	s_waitcnt lgkmcnt(7)
	v_pk_mul_f32 v[102:103], v[78:79], v[102:103]
	v_pk_mul_f32 v[96:97], v[110:111], v[96:97] op_sel_hi:[0,1]
	v_pk_fma_f32 v[100:101], v[76:77], v[100:101], v[102:103]
	v_pk_mul_f32 v[98:99], v[110:111], v[98:99] op_sel_hi:[0,1]
	v_add_f32_e32 v100, v100, v101
	v_pk_mul_f32 v[74:75], v[74:75], v[78:79]
	v_pk_fma_f32 v[42:43], v[76:77], v[42:43], v[96:97]
	v_add_f32_dpp v100, v100, v100 quad_perm:[1,0,3,2] row_mask:0xf bank_mask:0xf bound_ctrl:1
	ds_read_b128 v[38:41], v46 offset:8704
	v_pk_fma_f32 v[44:45], v[78:79], v[44:45], v[98:99]
	v_add_f32_dpp v100, v100, v100 quad_perm:[2,3,0,1] row_mask:0xf bank_mask:0xf bound_ctrl:1
	v_pk_fma_f32 v[72:73], v[72:73], v[76:77], v[74:75]
	ds_read_b128 v[18:21], v46 offset:7936
	v_add_f32_dpp v100, v100, v100 row_half_mirror row_mask:0xf bank_mask:0xf bound_ctrl:1
	v_add_f32_e32 v72, v72, v73
	ds_write_b32 v50, v72 offset:512
	v_add_f32_dpp v100, v100, v100 row_mirror row_mask:0xf bank_mask:0xf bound_ctrl:1
	v_pk_fma_f32 v[42:43], v[104:105], v[100:101], v[42:43] op_sel_hi:[1,0,1]
	v_pk_fma_f32 v[44:45], v[106:107], v[100:101], v[44:45] op_sel_hi:[1,0,1]
	ds_read_b128 v[30:33], v46 offset:8192
	ds_read_b32 v66, v47 offset:8448
	ds_read_b128 v[34:37], v46 offset:8960
	ds_read_b128 v[12:15], v46 offset:7680
	v_pk_mul_f32 v[94:95], v[94:95], v[44:45]
	s_nop 0
	v_pk_fma_f32 v[92:93], v[92:93], v[42:43], v[94:95]
	s_nop 0
	v_add_f32_e32 v92, v92, v93
	ds_write_b32 v50, v92 offset:768
	s_waitcnt lgkmcnt(8)
	v_pk_mul_f32 v[28:29], v[44:45], v[28:29]
	v_pk_mul_f32 v[8:9], v[64:65], v[8:9] op_sel_hi:[0,1]
	v_pk_fma_f32 v[26:27], v[42:43], v[26:27], v[28:29]
	v_pk_mul_f32 v[10:11], v[64:65], v[10:11] op_sel_hi:[0,1]
	v_add_f32_e32 v26, v26, v27
	ds_read_b128 v[84:87], v46 offset:10240
	v_pk_fma_f32 v[4:5], v[42:43], v[4:5], v[8:9]
	v_add_f32_dpp v26, v26, v26 quad_perm:[1,0,3,2] row_mask:0xf bank_mask:0xf bound_ctrl:1
	ds_read_b128 v[76:79], v46 offset:9472
	v_pk_fma_f32 v[6:7], v[44:45], v[6:7], v[10:11]
	v_add_f32_dpp v26, v26, v26 quad_perm:[2,3,0,1] row_mask:0xf bank_mask:0xf bound_ctrl:1
	ds_read_b128 v[80:83], v46 offset:9728
	ds_read_b32 v108, v47 offset:9984
	v_add_f32_dpp v26, v26, v26 row_half_mirror row_mask:0xf bank_mask:0xf bound_ctrl:1
	ds_read_b128 v[88:91], v46 offset:10496
	ds_read_b128 v[72:75], v46 offset:9216
	v_add_f32_dpp v26, v26, v26 row_mirror row_mask:0xf bank_mask:0xf bound_ctrl:1
	v_pk_fma_f32 v[4:5], v[22:23], v[26:27], v[4:5] op_sel_hi:[1,0,1]
	v_pk_fma_f32 v[6:7], v[24:25], v[26:27], v[6:7] op_sel_hi:[1,0,1]
	s_nop 0
	s_waitcnt lgkmcnt(7)
	v_pk_mul_f32 v[40:41], v[6:7], v[40:41]
	v_pk_mul_f32 v[30:31], v[66:67], v[30:31] op_sel_hi:[0,1]
	v_pk_fma_f32 v[38:39], v[4:5], v[38:39], v[40:41]
	v_pk_mul_f32 v[32:33], v[66:67], v[32:33] op_sel_hi:[0,1]
	v_add_f32_e32 v38, v38, v39
	v_pk_mul_f32 v[2:3], v[2:3], v[6:7]
	v_pk_fma_f32 v[18:19], v[4:5], v[18:19], v[30:31]
	v_add_f32_dpp v38, v38, v38 quad_perm:[1,0,3,2] row_mask:0xf bank_mask:0xf bound_ctrl:1
	ds_read_b128 v[100:103], v46 offset:11776
	v_pk_fma_f32 v[20:21], v[6:7], v[20:21], v[32:33]
	v_add_f32_dpp v38, v38, v38 quad_perm:[2,3,0,1] row_mask:0xf bank_mask:0xf bound_ctrl:1
	v_pk_fma_f32 v[0:1], v[0:1], v[4:5], v[2:3]
	ds_read_b128 v[42:45], v46 offset:11008
	v_add_f32_dpp v38, v38, v38 row_half_mirror row_mask:0xf bank_mask:0xf bound_ctrl:1
	v_add_f32_e32 v0, v0, v1
	ds_write_b32 v50, v0 offset:1024
	v_add_f32_dpp v38, v38, v38 row_mirror row_mask:0xf bank_mask:0xf bound_ctrl:1
	v_pk_fma_f32 v[18:19], v[34:35], v[38:39], v[18:19] op_sel_hi:[1,0,1]
	v_pk_fma_f32 v[20:21], v[36:37], v[38:39], v[20:21] op_sel_hi:[1,0,1]
	ds_read_b128 v[96:99], v46 offset:11264
	ds_read_b32 v110, v47 offset:11520
	ds_read_b128 v[104:107], v46 offset:12032
	ds_read_b128 v[92:95], v46 offset:10752
	s_waitcnt lgkmcnt(7)
; #define LAS __attribute__((address_space(3)))
; #define R4_ISSUE(cc, slot) do { const GAS float* g_ = gp + (size_t)(cc) * 2048; LAS float* l_ = ring + (slot) * 1536; _Pragma("unroll") for (int i_ = 0; i_ < 6; ++i_) \
;         __builtin_amdgcn_global_load_lds((const GAS unsigned*)(g_ + off[i_]), (LAS unsigned*)(l_ + i_ * 256), 16, 0, 0); } while (0)
; #define R4_LOAD(o, sb_) do { const LAS float* sb = (sb_); (o).r = *(const LAS f32x4*)(sb + cgp * 4); (o).w = *(const LAS f32x4*)(sb + 64 + cgp * 4); (o).k = *(const LAS f32x4*)(sb + 128 + cgp * 4); \
;         (o).a = *(const LAS f32x4*)(sb + 256 + cgp * 4); (o).b = *(const LAS f32x4*)(sb + 320 + cgp * 4); (o).vv = sb[192 + rq * 4 + rl]; asm volatile("" ::: "memory"); } while (0)
; __device__ __forceinline__ void rwkv_prompt_wave4(LAS float* ring, const GAS float* RW, int mbase, int h, int rq, GAS float* Sout, GAS float* YR, int lane) {
;     ...
;     for (int cc = 0; cc < 3; ++cc) R4_ISSUE(cc, cc);
;     float ykeep = 0.f;
;     R4Ops oA, oB, oC, oD;
;     asm volatile("s_waitcnt vmcnt(12)" ::: "memory");
;     R4_LOAD(oA, ring); R4_LOAD(oB, ring + 384);
;     for (int ci = 0; ci < NCH; ++ci) {
;         { const int cn = ci + 3; const int cl = cn < NCH ? cn : NCH - 1; R4_ISSUE(cl, cn % R4_NS); }
;         const LAS float* cb = ring + (ci % R4_NS) * 1536; const LAS float* nb = ring + ((ci + 1) % R4_NS) * 1536;
;         R4_LOAD(oC, cb + 768);  R4_STEP(oA, 0);
;         R4_LOAD(oD, cb + 1152); R4_STEP(oB, 1);
;         asm volatile("s_waitcnt vmcnt(12)" ::: "memory");
;         R4_LOAD(oA, nb);        R4_STEP(oC, 2);
;         R4_LOAD(oB, nb + 384);  R4_STEP(oD, 3);
;         if (cgp < 4) YR[(size_t)(mbase + ci * 4 + cgp) * 512 + h * 64 + rq * 4 + rl] = ykeep;
;     }
	v_pk_mul_f32 v[86:87], v[20:21], v[86:87]
	v_pk_mul_f32 v[80:81], v[108:109], v[80:81] op_sel_hi:[0,1]
	v_pk_fma_f32 v[84:85], v[18:19], v[84:85], v[86:87]
	v_pk_mul_f32 v[82:83], v[108:109], v[82:83] op_sel_hi:[0,1]
	v_add_f32_e32 v84, v84, v85
	v_pk_mul_f32 v[14:15], v[14:15], v[20:21]
	v_pk_fma_f32 v[76:77], v[18:19], v[76:77], v[80:81]
	v_add_f32_dpp v84, v84, v84 quad_perm:[1,0,3,2] row_mask:0xf bank_mask:0xf bound_ctrl:1
	ds_read_b128 v[26:29], v46 offset:13312
	v_pk_fma_f32 v[78:79], v[20:21], v[78:79], v[82:83]
	v_add_f32_dpp v84, v84, v84 quad_perm:[2,3,0,1] row_mask:0xf bank_mask:0xf bound_ctrl:1
	v_pk_fma_f32 v[12:13], v[12:13], v[18:19], v[14:15]
	ds_read_b128 v[4:7], v46 offset:12544
	v_add_f32_dpp v84, v84, v84 row_half_mirror row_mask:0xf bank_mask:0xf bound_ctrl:1
	v_add_f32_e32 v12, v12, v13
	ds_write_b32 v50, v12 offset:1280
	v_add_f32_dpp v84, v84, v84 row_mirror row_mask:0xf bank_mask:0xf bound_ctrl:1
	v_pk_fma_f32 v[76:77], v[88:89], v[84:85], v[76:77] op_sel_hi:[1,0,1]
	v_pk_fma_f32 v[78:79], v[90:91], v[84:85], v[78:79] op_sel_hi:[1,0,1]
	ds_read_b128 v[8:11], v46 offset:12800
	ds_read_b32 v64, v47 offset:13056
	ds_read_b128 v[22:25], v46 offset:13568
	ds_read_b128 v[0:3], v46 offset:12288
	s_waitcnt lgkmcnt(7)
	v_pk_mul_f32 v[102:103], v[78:79], v[102:103]
	v_pk_mul_f32 v[96:97], v[110:111], v[96:97] op_sel_hi:[0,1]
	v_pk_fma_f32 v[100:101], v[76:77], v[100:101], v[102:103]
	v_pk_mul_f32 v[98:99], v[110:111], v[98:99] op_sel_hi:[0,1]
	v_add_f32_e32 v100, v100, v101
	v_pk_mul_f32 v[74:75], v[74:75], v[78:79]
	v_pk_fma_f32 v[42:43], v[76:77], v[42:43], v[96:97]
	v_add_f32_dpp v100, v100, v100 quad_perm:[1,0,3,2] row_mask:0xf bank_mask:0xf bound_ctrl:1
	ds_read_b128 v[38:41], v46 offset:14848
	v_pk_fma_f32 v[44:45], v[78:79], v[44:45], v[98:99]
	v_add_f32_dpp v100, v100, v100 quad_perm:[2,3,0,1] row_mask:0xf bank_mask:0xf bound_ctrl:1
	v_pk_fma_f32 v[72:73], v[72:73], v[76:77], v[74:75]
	ds_read_b128 v[18:21], v46 offset:14080
	v_add_f32_dpp v100, v100, v100 row_half_mirror row_mask:0xf bank_mask:0xf bound_ctrl:1
	v_add_f32_e32 v72, v72, v73
	ds_write_b32 v50, v72 offset:1536
	v_add_f32_dpp v100, v100, v100 row_mirror row_mask:0xf bank_mask:0xf bound_ctrl:1
	v_pk_fma_f32 v[42:43], v[104:105], v[100:101], v[42:43] op_sel_hi:[1,0,1]
	v_pk_fma_f32 v[44:45], v[106:107], v[100:101], v[44:45] op_sel_hi:[1,0,1]
	ds_read_b128 v[30:33], v46 offset:14336
	ds_read_b32 v66, v47 offset:14592
	ds_read_b128 v[34:37], v46 offset:15104
	ds_read_b128 v[12:15], v46 offset:13824
	v_pk_mul_f32 v[94:95], v[94:95], v[44:45]
	s_nop 0
	v_pk_fma_f32 v[92:93], v[92:93], v[42:43], v[94:95]
	s_nop 0
	v_add_f32_e32 v92, v92, v93
	ds_write_b32 v50, v92 offset:1792
	s_waitcnt lgkmcnt(8)
	v_pk_mul_f32 v[28:29], v[44:45], v[28:29]
	v_pk_mul_f32 v[8:9], v[64:65], v[8:9] op_sel_hi:[0,1]
	v_pk_fma_f32 v[26:27], v[42:43], v[26:27], v[28:29]
	v_pk_mul_f32 v[10:11], v[64:65], v[10:11] op_sel_hi:[0,1]
	v_add_f32_e32 v26, v26, v27
	ds_read_b128 v[84:87], v46 offset:16384
	v_pk_fma_f32 v[4:5], v[42:43], v[4:5], v[8:9]
	v_add_f32_dpp v26, v26, v26 quad_perm:[1,0,3,2] row_mask:0xf bank_mask:0xf bound_ctrl:1
	ds_read_b128 v[76:79], v46 offset:15616
	v_pk_fma_f32 v[6:7], v[44:45], v[6:7], v[10:11]
	v_add_f32_dpp v26, v26, v26 quad_perm:[2,3,0,1] row_mask:0xf bank_mask:0xf bound_ctrl:1
	ds_read_b128 v[80:83], v46 offset:15872
	ds_read_b32 v108, v47 offset:16128
	v_add_f32_dpp v26, v26, v26 row_half_mirror row_mask:0xf bank_mask:0xf bound_ctrl:1
	ds_read_b128 v[88:91], v46 offset:16640
	ds_read_b128 v[72:75], v46 offset:15360
	v_add_f32_dpp v26, v26, v26 row_mirror row_mask:0xf bank_mask:0xf bound_ctrl:1
	v_pk_fma_f32 v[4:5], v[22:23], v[26:27], v[4:5] op_sel_hi:[1,0,1]
	v_pk_fma_f32 v[6:7], v[24:25], v[26:27], v[6:7] op_sel_hi:[1,0,1]
	s_nop 0
	s_waitcnt lgkmcnt(7)
	v_pk_mul_f32 v[40:41], v[6:7], v[40:41]
	v_pk_mul_f32 v[30:31], v[66:67], v[30:31] op_sel_hi:[0,1]
	v_pk_fma_f32 v[38:39], v[4:5], v[38:39], v[40:41]
	v_pk_mul_f32 v[32:33], v[66:67], v[32:33] op_sel_hi:[0,1]
	v_add_f32_e32 v38, v38, v39
	v_pk_mul_f32 v[2:3], v[2:3], v[6:7]
	v_pk_fma_f32 v[18:19], v[4:5], v[18:19], v[30:31]
	v_add_f32_dpp v38, v38, v38 quad_perm:[1,0,3,2] row_mask:0xf bank_mask:0xf bound_ctrl:1
	ds_read_b128 v[100:103], v46 offset:17920
	v_pk_fma_f32 v[20:21], v[6:7], v[20:21], v[32:33]
	v_add_f32_dpp v38, v38, v38 quad_perm:[2,3,0,1] row_mask:0xf bank_mask:0xf bound_ctrl:1
	v_pk_fma_f32 v[0:1], v[0:1], v[4:5], v[2:3]
	ds_read_b128 v[42:45], v46 offset:17152
	v_add_f32_dpp v38, v38, v38 row_half_mirror row_mask:0xf bank_mask:0xf bound_ctrl:1
	v_add_f32_e32 v0, v0, v1
	ds_write_b32 v50, v0 offset:2048
	v_add_f32_dpp v38, v38, v38 row_mirror row_mask:0xf bank_mask:0xf bound_ctrl:1
	v_pk_fma_f32 v[18:19], v[34:35], v[38:39], v[18:19] op_sel_hi:[1,0,1]
	v_pk_fma_f32 v[20:21], v[36:37], v[38:39], v[20:21] op_sel_hi:[1,0,1]
	ds_read_b128 v[96:99], v46 offset:17408
	ds_read_b32 v110, v47 offset:17664
	ds_read_b128 v[104:107], v46 offset:18176
	ds_read_b128 v[92:95], v46 offset:16896
	s_waitcnt lgkmcnt(7)
; #define LAS __attribute__((address_space(3)))
; #define R4_ISSUE(cc, slot) do { const GAS float* g_ = gp + (size_t)(cc) * 2048; LAS float* l_ = ring + (slot) * 1536; _Pragma("unroll") for (int i_ = 0; i_ < 6; ++i_) \
;         __builtin_amdgcn_global_load_lds((const GAS unsigned*)(g_ + off[i_]), (LAS unsigned*)(l_ + i_ * 256), 16, 0, 0); } while (0)
; #define R4_LOAD(o, sb_) do { const LAS float* sb = (sb_); (o).r = *(const LAS f32x4*)(sb + cgp * 4); (o).w = *(const LAS f32x4*)(sb + 64 + cgp * 4); (o).k = *(const LAS f32x4*)(sb + 128 + cgp * 4); \
;         (o).a = *(const LAS f32x4*)(sb + 256 + cgp * 4); (o).b = *(const LAS f32x4*)(sb + 320 + cgp * 4); (o).vv = sb[192 + rq * 4 + rl]; asm volatile("" ::: "memory"); } while (0)
; __device__ __forceinline__ void rwkv_prompt_wave4(LAS float* ring, const GAS float* RW, int mbase, int h, int rq, GAS float* Sout, GAS float* YR, int lane) {
;     ...
;     for (int cc = 0; cc < 3; ++cc) R4_ISSUE(cc, cc);
;     float ykeep = 0.f;
;     R4Ops oA, oB, oC, oD;
;     asm volatile("s_waitcnt vmcnt(12)" ::: "memory");
;     R4_LOAD(oA, ring); R4_LOAD(oB, ring + 384);
;     for (int ci = 0; ci < NCH; ++ci) {
;         { const int cn = ci + 3; const int cl = cn < NCH ? cn : NCH - 1; R4_ISSUE(cl, cn % R4_NS); }
;         const LAS float* cb = ring + (ci % R4_NS) * 1536; const LAS float* nb = ring + ((ci + 1) % R4_NS) * 1536;
;         R4_LOAD(oC, cb + 768);  R4_STEP(oA, 0);
;         R4_LOAD(oD, cb + 1152); R4_STEP(oB, 1);
;         asm volatile("s_waitcnt vmcnt(12)" ::: "memory");
;         R4_LOAD(oA, nb);        R4_STEP(oC, 2);
;         R4_LOAD(oB, nb + 384);  R4_STEP(oD, 3);
;         if (cgp < 4) YR[(size_t)(mbase + ci * 4 + cgp) * 512 + h * 64 + rq * 4 + rl] = ykeep;
;     }
	v_pk_mul_f32 v[86:87], v[20:21], v[86:87]
	v_pk_mul_f32 v[80:81], v[108:109], v[80:81] op_sel_hi:[0,1]
	v_pk_fma_f32 v[84:85], v[18:19], v[84:85], v[86:87]
	v_pk_mul_f32 v[82:83], v[108:109], v[82:83] op_sel_hi:[0,1]
	v_add_f32_e32 v84, v84, v85
	v_pk_mul_f32 v[14:15], v[14:15], v[20:21]
	v_pk_fma_f32 v[76:77], v[18:19], v[76:77], v[80:81]
	v_add_f32_dpp v84, v84, v84 quad_perm:[1,0,3,2] row_mask:0xf bank_mask:0xf bound_ctrl:1
	ds_read_b128 v[26:29], v46 offset:19456
	v_pk_fma_f32 v[78:79], v[20:21], v[78:79], v[82:83]
	v_add_f32_dpp v84, v84, v84 quad_perm:[2,3,0,1] row_mask:0xf bank_mask:0xf bound_ctrl:1
	v_pk_fma_f32 v[12:13], v[12:13], v[18:19], v[14:15]
	ds_read_b128 v[4:7], v46 offset:18688
	v_add_f32_dpp v84, v84, v84 row_half_mirror row_mask:0xf bank_mask:0xf bound_ctrl:1
	v_add_f32_e32 v12, v12, v13
	ds_write_b32 v50, v12 offset:2304
	v_add_f32_dpp v84, v84, v84 row_mirror row_mask:0xf bank_mask:0xf bound_ctrl:1
	v_pk_fma_f32 v[76:77], v[88:89], v[84:85], v[76:77] op_sel_hi:[1,0,1]
	v_pk_fma_f32 v[78:79], v[90:91], v[84:85], v[78:79] op_sel_hi:[1,0,1]
	ds_read_b128 v[8:11], v46 offset:18944
	ds_read_b32 v64, v47 offset:19200
	ds_read_b128 v[22:25], v46 offset:19712
	ds_read_b128 v[0:3], v46 offset:18432
	s_waitcnt lgkmcnt(7)
	v_pk_mul_f32 v[102:103], v[78:79], v[102:103]
	v_pk_mul_f32 v[96:97], v[110:111], v[96:97] op_sel_hi:[0,1]
	v_pk_fma_f32 v[100:101], v[76:77], v[100:101], v[102:103]
	v_pk_mul_f32 v[98:99], v[110:111], v[98:99] op_sel_hi:[0,1]
	v_add_f32_e32 v100, v100, v101
	v_pk_mul_f32 v[74:75], v[74:75], v[78:79]
	v_pk_fma_f32 v[42:43], v[76:77], v[42:43], v[96:97]
	v_add_f32_dpp v100, v100, v100 quad_perm:[1,0,3,2] row_mask:0xf bank_mask:0xf bound_ctrl:1
	ds_read_b128 v[38:41], v46 offset:20992
	v_pk_fma_f32 v[44:45], v[78:79], v[44:45], v[98:99]
	v_add_f32_dpp v100, v100, v100 quad_perm:[2,3,0,1] row_mask:0xf bank_mask:0xf bound_ctrl:1
	v_pk_fma_f32 v[72:73], v[72:73], v[76:77], v[74:75]
	ds_read_b128 v[18:21], v46 offset:20224
	v_add_f32_dpp v100, v100, v100 row_half_mirror row_mask:0xf bank_mask:0xf bound_ctrl:1
	v_add_f32_e32 v72, v72, v73
	ds_write_b32 v50, v72 offset:2560
	v_add_f32_dpp v100, v100, v100 row_mirror row_mask:0xf bank_mask:0xf bound_ctrl:1
	v_pk_fma_f32 v[42:43], v[104:105], v[100:101], v[42:43] op_sel_hi:[1,0,1]
	v_pk_fma_f32 v[44:45], v[106:107], v[100:101], v[44:45] op_sel_hi:[1,0,1]
	ds_read_b128 v[30:33], v46 offset:20480
	ds_read_b32 v66, v47 offset:20736
	ds_read_b128 v[34:37], v46 offset:21248
	ds_read_b128 v[12:15], v46 offset:19968
	v_pk_mul_f32 v[94:95], v[94:95], v[44:45]
	s_nop 0
	v_pk_fma_f32 v[92:93], v[92:93], v[42:43], v[94:95]
	s_nop 0
	v_add_f32_e32 v92, v92, v93
	ds_write_b32 v50, v92 offset:2816
	s_waitcnt lgkmcnt(8)
	v_pk_mul_f32 v[28:29], v[44:45], v[28:29]
	v_pk_mul_f32 v[8:9], v[64:65], v[8:9] op_sel_hi:[0,1]
	v_pk_fma_f32 v[26:27], v[42:43], v[26:27], v[28:29]
	v_pk_mul_f32 v[10:11], v[64:65], v[10:11] op_sel_hi:[0,1]
	v_add_f32_e32 v26, v26, v27
	ds_read_b128 v[84:87], v46 offset:22528
	v_pk_fma_f32 v[4:5], v[42:43], v[4:5], v[8:9]
	v_add_f32_dpp v26, v26, v26 quad_perm:[1,0,3,2] row_mask:0xf bank_mask:0xf bound_ctrl:1
	ds_read_b128 v[76:79], v46 offset:21760
	v_pk_fma_f32 v[6:7], v[44:45], v[6:7], v[10:11]
	v_add_f32_dpp v26, v26, v26 quad_perm:[2,3,0,1] row_mask:0xf bank_mask:0xf bound_ctrl:1
	ds_read_b128 v[80:83], v46 offset:22016
	ds_read_b32 v108, v47 offset:22272
	v_add_f32_dpp v26, v26, v26 row_half_mirror row_mask:0xf bank_mask:0xf bound_ctrl:1
	ds_read_b128 v[88:91], v46 offset:22784
	ds_read_b128 v[72:75], v46 offset:21504
	v_add_f32_dpp v26, v26, v26 row_mirror row_mask:0xf bank_mask:0xf bound_ctrl:1
	v_pk_fma_f32 v[4:5], v[22:23], v[26:27], v[4:5] op_sel_hi:[1,0,1]
	v_pk_fma_f32 v[6:7], v[24:25], v[26:27], v[6:7] op_sel_hi:[1,0,1]
	s_nop 0
	s_waitcnt lgkmcnt(7)
	v_pk_mul_f32 v[40:41], v[6:7], v[40:41]
	v_pk_mul_f32 v[30:31], v[66:67], v[30:31] op_sel_hi:[0,1]
	v_pk_fma_f32 v[38:39], v[4:5], v[38:39], v[40:41]
	v_pk_mul_f32 v[32:33], v[66:67], v[32:33] op_sel_hi:[0,1]
	v_add_f32_e32 v38, v38, v39
	v_pk_mul_f32 v[2:3], v[2:3], v[6:7]
	v_pk_fma_f32 v[18:19], v[4:5], v[18:19], v[30:31]
	v_add_f32_dpp v38, v38, v38 quad_perm:[1,0,3,2] row_mask:0xf bank_mask:0xf bound_ctrl:1
	ds_read_b128 v[100:103], v46 offset:24064
	v_pk_fma_f32 v[20:21], v[6:7], v[20:21], v[32:33]
	v_add_f32_dpp v38, v38, v38 quad_perm:[2,3,0,1] row_mask:0xf bank_mask:0xf bound_ctrl:1
	v_pk_fma_f32 v[0:1], v[0:1], v[4:5], v[2:3]
	ds_read_b128 v[42:45], v46 offset:23296
	v_add_f32_dpp v38, v38, v38 row_half_mirror row_mask:0xf bank_mask:0xf bound_ctrl:1
	v_add_f32_e32 v0, v0, v1
	ds_write_b32 v50, v0 offset:3072
	v_add_f32_dpp v38, v38, v38 row_mirror row_mask:0xf bank_mask:0xf bound_ctrl:1
	v_pk_fma_f32 v[18:19], v[34:35], v[38:39], v[18:19] op_sel_hi:[1,0,1]
	v_pk_fma_f32 v[20:21], v[36:37], v[38:39], v[20:21] op_sel_hi:[1,0,1]
	ds_read_b128 v[96:99], v46 offset:23552
	ds_read_b32 v110, v47 offset:23808
	ds_read_b128 v[104:107], v46 offset:24320
	ds_read_b128 v[92:95], v46 offset:23040
	s_waitcnt lgkmcnt(7)
; #define LAS __attribute__((address_space(3)))
; #define R4_ISSUE(cc, slot) do { const GAS float* g_ = gp + (size_t)(cc) * 2048; LAS float* l_ = ring + (slot) * 1536; _Pragma("unroll") for (int i_ = 0; i_ < 6; ++i_) \
;         __builtin_amdgcn_global_load_lds((const GAS unsigned*)(g_ + off[i_]), (LAS unsigned*)(l_ + i_ * 256), 16, 0, 0); } while (0)
; #define R4_LOAD(o, sb_) do { const LAS float* sb = (sb_); (o).r = *(const LAS f32x4*)(sb + cgp * 4); (o).w = *(const LAS f32x4*)(sb + 64 + cgp * 4); (o).k = *(const LAS f32x4*)(sb + 128 + cgp * 4); \
;         (o).a = *(const LAS f32x4*)(sb + 256 + cgp * 4); (o).b = *(const LAS f32x4*)(sb + 320 + cgp * 4); (o).vv = sb[192 + rq * 4 + rl]; asm volatile("" ::: "memory"); } while (0)
; __device__ __forceinline__ void rwkv_prompt_wave4(LAS float* ring, const GAS float* RW, int mbase, int h, int rq, GAS float* Sout, GAS float* YR, int lane) {
;     ...
;     for (int cc = 0; cc < 3; ++cc) R4_ISSUE(cc, cc);
;     float ykeep = 0.f;
;     R4Ops oA, oB, oC, oD;
;     asm volatile("s_waitcnt vmcnt(12)" ::: "memory");
;     R4_LOAD(oA, ring); R4_LOAD(oB, ring + 384);
;     for (int ci = 0; ci < NCH; ++ci) {
;         { const int cn = ci + 3; const int cl = cn < NCH ? cn : NCH - 1; R4_ISSUE(cl, cn % R4_NS); }
;         const LAS float* cb = ring + (ci % R4_NS) * 1536; const LAS float* nb = ring + ((ci + 1) % R4_NS) * 1536;
;         R4_LOAD(oC, cb + 768);  R4_STEP(oA, 0);
;         R4_LOAD(oD, cb + 1152); R4_STEP(oB, 1);
;         asm volatile("s_waitcnt vmcnt(12)" ::: "memory");
;         R4_LOAD(oA, nb);        R4_STEP(oC, 2);
;         R4_LOAD(oB, nb + 384);  R4_STEP(oD, 3);
;         if (cgp < 4) YR[(size_t)(mbase + ci * 4 + cgp) * 512 + h * 64 + rq * 4 + rl] = ykeep;
;     }
	v_pk_mul_f32 v[86:87], v[20:21], v[86:87]
	v_pk_mul_f32 v[80:81], v[108:109], v[80:81] op_sel_hi:[0,1]
	v_pk_fma_f32 v[84:85], v[18:19], v[84:85], v[86:87]
	v_pk_mul_f32 v[82:83], v[108:109], v[82:83] op_sel_hi:[0,1]
	v_add_f32_e32 v84, v84, v85
	v_pk_mul_f32 v[14:15], v[14:15], v[20:21]
	v_pk_fma_f32 v[76:77], v[18:19], v[76:77], v[80:81]
	v_add_f32_dpp v84, v84, v84 quad_perm:[1,0,3,2] row_mask:0xf bank_mask:0xf bound_ctrl:1
	ds_read_b128 v[26:29], v46 offset:25600
	v_pk_fma_f32 v[78:79], v[20:21], v[78:79], v[82:83]
	v_add_f32_dpp v84, v84, v84 quad_perm:[2,3,0,1] row_mask:0xf bank_mask:0xf bound_ctrl:1
	v_pk_fma_f32 v[12:13], v[12:13], v[18:19], v[14:15]
	ds_read_b128 v[4:7], v46 offset:24832
	v_add_f32_dpp v84, v84, v84 row_half_mirror row_mask:0xf bank_mask:0xf bound_ctrl:1
	v_add_f32_e32 v12, v12, v13
	ds_write_b32 v50, v12 offset:3328
	v_add_f32_dpp v84, v84, v84 row_mirror row_mask:0xf bank_mask:0xf bound_ctrl:1
	v_pk_fma_f32 v[76:77], v[88:89], v[84:85], v[76:77] op_sel_hi:[1,0,1]
	v_pk_fma_f32 v[78:79], v[90:91], v[84:85], v[78:79] op_sel_hi:[1,0,1]
	ds_read_b128 v[8:11], v46 offset:25088
	ds_read_b32 v64, v47 offset:25344
	ds_read_b128 v[22:25], v46 offset:25856
	ds_read_b128 v[0:3], v46 offset:24576
	s_waitcnt lgkmcnt(7)
	v_pk_mul_f32 v[102:103], v[78:79], v[102:103]
	v_pk_mul_f32 v[96:97], v[110:111], v[96:97] op_sel_hi:[0,1]
	v_pk_fma_f32 v[100:101], v[76:77], v[100:101], v[102:103]
	v_pk_mul_f32 v[98:99], v[110:111], v[98:99] op_sel_hi:[0,1]
	v_add_f32_e32 v100, v100, v101
	v_pk_mul_f32 v[74:75], v[74:75], v[78:79]
	v_pk_fma_f32 v[42:43], v[76:77], v[42:43], v[96:97]
	v_add_f32_dpp v100, v100, v100 quad_perm:[1,0,3,2] row_mask:0xf bank_mask:0xf bound_ctrl:1
	ds_read_b128 v[38:41], v46 offset:27136
	v_pk_fma_f32 v[44:45], v[78:79], v[44:45], v[98:99]
	v_add_f32_dpp v100, v100, v100 quad_perm:[2,3,0,1] row_mask:0xf bank_mask:0xf bound_ctrl:1
	v_pk_fma_f32 v[72:73], v[72:73], v[76:77], v[74:75]
	ds_read_b128 v[18:21], v46 offset:26368
	v_add_f32_dpp v100, v100, v100 row_half_mirror row_mask:0xf bank_mask:0xf bound_ctrl:1
	v_add_f32_e32 v72, v72, v73
	ds_write_b32 v50, v72 offset:3584
	v_add_f32_dpp v100, v100, v100 row_mirror row_mask:0xf bank_mask:0xf bound_ctrl:1
	v_pk_fma_f32 v[42:43], v[104:105], v[100:101], v[42:43] op_sel_hi:[1,0,1]
	v_pk_fma_f32 v[44:45], v[106:107], v[100:101], v[44:45] op_sel_hi:[1,0,1]
	ds_read_b128 v[30:33], v46 offset:26624
	ds_read_b32 v66, v47 offset:26880
	ds_read_b128 v[34:37], v46 offset:27392
	ds_read_b128 v[12:15], v46 offset:26112
	v_pk_mul_f32 v[94:95], v[94:95], v[44:45]
	s_nop 0
	v_pk_fma_f32 v[92:93], v[92:93], v[42:43], v[94:95]
	s_nop 0
	v_add_f32_e32 v92, v92, v93
	ds_write_b32 v50, v92 offset:3840
	s_waitcnt lgkmcnt(0)
	s_barrier
	s_waitcnt lgkmcnt(8)
	v_pk_mul_f32 v[28:29], v[44:45], v[28:29]
	v_pk_mul_f32 v[8:9], v[64:65], v[8:9] op_sel_hi:[0,1]
	v_pk_fma_f32 v[26:27], v[42:43], v[26:27], v[28:29]
	v_pk_mul_f32 v[10:11], v[64:65], v[10:11] op_sel_hi:[0,1]
	v_add_f32_e32 v26, v26, v27
	ds_read_b128 v[84:87], v46 offset:28672
	v_pk_fma_f32 v[4:5], v[42:43], v[4:5], v[8:9]
	v_add_f32_dpp v26, v26, v26 quad_perm:[1,0,3,2] row_mask:0xf bank_mask:0xf bound_ctrl:1
	ds_read_b128 v[76:79], v46 offset:27904
	v_pk_fma_f32 v[6:7], v[44:45], v[6:7], v[10:11]
	v_add_f32_dpp v26, v26, v26 quad_perm:[2,3,0,1] row_mask:0xf bank_mask:0xf bound_ctrl:1
	ds_read_b128 v[80:83], v46 offset:28160
	ds_read_b32 v108, v47 offset:28416
	v_add_f32_dpp v26, v26, v26 row_half_mirror row_mask:0xf bank_mask:0xf bound_ctrl:1
	ds_read_b128 v[88:91], v46 offset:28928
	ds_read_b128 v[72:75], v46 offset:27648
	v_add_f32_dpp v26, v26, v26 row_mirror row_mask:0xf bank_mask:0xf bound_ctrl:1
	v_pk_fma_f32 v[4:5], v[22:23], v[26:27], v[4:5] op_sel_hi:[1,0,1]
	v_pk_fma_f32 v[6:7], v[24:25], v[26:27], v[6:7] op_sel_hi:[1,0,1]
	s_nop 0
	s_waitcnt lgkmcnt(7)
	v_pk_mul_f32 v[40:41], v[6:7], v[40:41]
	v_pk_mul_f32 v[30:31], v[66:67], v[30:31] op_sel_hi:[0,1]
	v_pk_fma_f32 v[38:39], v[4:5], v[38:39], v[40:41]
	v_pk_mul_f32 v[32:33], v[66:67], v[32:33] op_sel_hi:[0,1]
	v_add_f32_e32 v38, v38, v39
	v_pk_mul_f32 v[2:3], v[2:3], v[6:7]
	v_pk_fma_f32 v[18:19], v[4:5], v[18:19], v[30:31]
	v_add_f32_dpp v38, v38, v38 quad_perm:[1,0,3,2] row_mask:0xf bank_mask:0xf bound_ctrl:1
	ds_read_b128 v[100:103], v46 offset:30208
	v_pk_fma_f32 v[20:21], v[6:7], v[20:21], v[32:33]
	v_add_f32_dpp v38, v38, v38 quad_perm:[2,3,0,1] row_mask:0xf bank_mask:0xf bound_ctrl:1
	v_pk_fma_f32 v[0:1], v[0:1], v[4:5], v[2:3]
	ds_read_b128 v[42:45], v46 offset:29440
	v_add_f32_dpp v38, v38, v38 row_half_mirror row_mask:0xf bank_mask:0xf bound_ctrl:1
	v_add_f32_e32 v0, v0, v1
	ds_write_b32 v50, v0 offset:4096
	v_add_f32_dpp v38, v38, v38 row_mirror row_mask:0xf bank_mask:0xf bound_ctrl:1
	v_pk_fma_f32 v[18:19], v[34:35], v[38:39], v[18:19] op_sel_hi:[1,0,1]
	v_pk_fma_f32 v[20:21], v[36:37], v[38:39], v[20:21] op_sel_hi:[1,0,1]
	ds_read_b128 v[96:99], v46 offset:29696
	ds_read_b32 v110, v47 offset:29952
	ds_read_b128 v[104:107], v46 offset:30464
	ds_read_b128 v[92:95], v46 offset:29184
	s_waitcnt lgkmcnt(7)
; #define LAS __attribute__((address_space(3)))
; #define R4_ISSUE(cc, slot) do { const GAS float* g_ = gp + (size_t)(cc) * 2048; LAS float* l_ = ring + (slot) * 1536; _Pragma("unroll") for (int i_ = 0; i_ < 6; ++i_) \
;         __builtin_amdgcn_global_load_lds((const GAS unsigned*)(g_ + off[i_]), (LAS unsigned*)(l_ + i_ * 256), 16, 0, 0); } while (0)
; #define R4_LOAD(o, sb_) do { const LAS float* sb = (sb_); (o).r = *(const LAS f32x4*)(sb + cgp * 4); (o).w = *(const LAS f32x4*)(sb + 64 + cgp * 4); (o).k = *(const LAS f32x4*)(sb + 128 + cgp * 4); \
;         (o).a = *(const LAS f32x4*)(sb + 256 + cgp * 4); (o).b = *(const LAS f32x4*)(sb + 320 + cgp * 4); (o).vv = sb[192 + rq * 4 + rl]; asm volatile("" ::: "memory"); } while (0)
; __device__ __forceinline__ void rwkv_prompt_wave4(LAS float* ring, const GAS float* RW, int mbase, int h, int rq, GAS float* Sout, GAS float* YR, int lane) {
;     ...
;     for (int cc = 0; cc < 3; ++cc) R4_ISSUE(cc, cc);
;     float ykeep = 0.f;
;     R4Ops oA, oB, oC, oD;
;     asm volatile("s_waitcnt vmcnt(12)" ::: "memory");
;     R4_LOAD(oA, ring); R4_LOAD(oB, ring + 384);
;     for (int ci = 0; ci < NCH; ++ci) {
;         { const int cn = ci + 3; const int cl = cn < NCH ? cn : NCH - 1; R4_ISSUE(cl, cn % R4_NS); }
;         const LAS float* cb = ring + (ci % R4_NS) * 1536; const LAS float* nb = ring + ((ci + 1) % R4_NS) * 1536;
;         R4_LOAD(oC, cb + 768);  R4_STEP(oA, 0);
;         R4_LOAD(oD, cb + 1152); R4_STEP(oB, 1);
;         asm volatile("s_waitcnt vmcnt(12)" ::: "memory");
;         R4_LOAD(oA, nb);        R4_STEP(oC, 2);
;         R4_LOAD(oB, nb + 384);  R4_STEP(oD, 3);
;         if (cgp < 4) YR[(size_t)(mbase + ci * 4 + cgp) * 512 + h * 64 + rq * 4 + rl] = ykeep;
;     }
	v_pk_mul_f32 v[86:87], v[20:21], v[86:87]
	v_pk_mul_f32 v[80:81], v[108:109], v[80:81] op_sel_hi:[0,1]
	v_pk_fma_f32 v[84:85], v[18:19], v[84:85], v[86:87]
	v_pk_mul_f32 v[82:83], v[108:109], v[82:83] op_sel_hi:[0,1]
	v_add_f32_e32 v84, v84, v85
	v_pk_mul_f32 v[14:15], v[14:15], v[20:21]
	v_pk_fma_f32 v[76:77], v[18:19], v[76:77], v[80:81]
	v_add_f32_dpp v84, v84, v84 quad_perm:[1,0,3,2] row_mask:0xf bank_mask:0xf bound_ctrl:1
	ds_read_b128 v[26:29], v46 offset:31744
	v_pk_fma_f32 v[78:79], v[20:21], v[78:79], v[82:83]
	v_add_f32_dpp v84, v84, v84 quad_perm:[2,3,0,1] row_mask:0xf bank_mask:0xf bound_ctrl:1
	v_pk_fma_f32 v[12:13], v[12:13], v[18:19], v[14:15]
	ds_read_b128 v[4:7], v46 offset:30976
	v_add_f32_dpp v84, v84, v84 row_half_mirror row_mask:0xf bank_mask:0xf bound_ctrl:1
	v_add_f32_e32 v12, v12, v13
	ds_write_b32 v50, v12 offset:4352
	v_add_f32_dpp v84, v84, v84 row_mirror row_mask:0xf bank_mask:0xf bound_ctrl:1
	v_pk_fma_f32 v[76:77], v[88:89], v[84:85], v[76:77] op_sel_hi:[1,0,1]
	v_pk_fma_f32 v[78:79], v[90:91], v[84:85], v[78:79] op_sel_hi:[1,0,1]
	ds_read_b128 v[8:11], v46 offset:31232
	ds_read_b32 v64, v47 offset:31488
	ds_read_b128 v[22:25], v46 offset:32000
	ds_read_b128 v[0:3], v46 offset:30720
	s_waitcnt lgkmcnt(7)
	v_pk_mul_f32 v[102:103], v[78:79], v[102:103]
	v_pk_mul_f32 v[96:97], v[110:111], v[96:97] op_sel_hi:[0,1]
	v_pk_fma_f32 v[100:101], v[76:77], v[100:101], v[102:103]
	v_pk_mul_f32 v[98:99], v[110:111], v[98:99] op_sel_hi:[0,1]
	v_add_f32_e32 v100, v100, v101
	v_pk_mul_f32 v[74:75], v[74:75], v[78:79]
	v_pk_fma_f32 v[42:43], v[76:77], v[42:43], v[96:97]
	v_add_f32_dpp v100, v100, v100 quad_perm:[1,0,3,2] row_mask:0xf bank_mask:0xf bound_ctrl:1
	ds_read_b128 v[38:41], v46 offset:33280
	v_pk_fma_f32 v[44:45], v[78:79], v[44:45], v[98:99]
	v_add_f32_dpp v100, v100, v100 quad_perm:[2,3,0,1] row_mask:0xf bank_mask:0xf bound_ctrl:1
	v_pk_fma_f32 v[72:73], v[72:73], v[76:77], v[74:75]
	ds_read_b128 v[18:21], v46 offset:32512
	v_add_f32_dpp v100, v100, v100 row_half_mirror row_mask:0xf bank_mask:0xf bound_ctrl:1
	v_add_f32_e32 v72, v72, v73
	ds_write_b32 v50, v72 offset:4608
	v_add_f32_dpp v100, v100, v100 row_mirror row_mask:0xf bank_mask:0xf bound_ctrl:1
	v_pk_fma_f32 v[42:43], v[104:105], v[100:101], v[42:43] op_sel_hi:[1,0,1]
	v_pk_fma_f32 v[44:45], v[106:107], v[100:101], v[44:45] op_sel_hi:[1,0,1]
	ds_read_b128 v[30:33], v46 offset:32768
	ds_read_b32 v66, v47 offset:33024
	ds_read_b128 v[34:37], v46 offset:33536
	ds_read_b128 v[12:15], v46 offset:32256
	v_pk_mul_f32 v[94:95], v[94:95], v[44:45]
	s_nop 0
	v_pk_fma_f32 v[92:93], v[92:93], v[42:43], v[94:95]
	s_nop 0
	v_add_f32_e32 v92, v92, v93
	ds_write_b32 v50, v92 offset:4864
	s_waitcnt lgkmcnt(8)
	v_pk_mul_f32 v[28:29], v[44:45], v[28:29]
	v_pk_mul_f32 v[8:9], v[64:65], v[8:9] op_sel_hi:[0,1]
	v_pk_fma_f32 v[26:27], v[42:43], v[26:27], v[28:29]
	v_pk_mul_f32 v[10:11], v[64:65], v[10:11] op_sel_hi:[0,1]
	v_add_f32_e32 v26, v26, v27
	ds_read_b128 v[84:87], v46 offset:34816
	v_pk_fma_f32 v[4:5], v[42:43], v[4:5], v[8:9]
	v_add_f32_dpp v26, v26, v26 quad_perm:[1,0,3,2] row_mask:0xf bank_mask:0xf bound_ctrl:1
	ds_read_b128 v[76:79], v46 offset:34048
	v_pk_fma_f32 v[6:7], v[44:45], v[6:7], v[10:11]
	v_add_f32_dpp v26, v26, v26 quad_perm:[2,3,0,1] row_mask:0xf bank_mask:0xf bound_ctrl:1
	ds_read_b128 v[80:83], v46 offset:34304
	ds_read_b32 v108, v47 offset:34560
	v_add_f32_dpp v26, v26, v26 row_half_mirror row_mask:0xf bank_mask:0xf bound_ctrl:1
	ds_read_b128 v[88:91], v46 offset:35072
	ds_read_b128 v[72:75], v46 offset:33792
	v_add_f32_dpp v26, v26, v26 row_mirror row_mask:0xf bank_mask:0xf bound_ctrl:1
	v_pk_fma_f32 v[4:5], v[22:23], v[26:27], v[4:5] op_sel_hi:[1,0,1]
	v_pk_fma_f32 v[6:7], v[24:25], v[26:27], v[6:7] op_sel_hi:[1,0,1]
	s_nop 0
	s_waitcnt lgkmcnt(7)
	v_pk_mul_f32 v[40:41], v[6:7], v[40:41]
	v_pk_mul_f32 v[30:31], v[66:67], v[30:31] op_sel_hi:[0,1]
	v_pk_fma_f32 v[38:39], v[4:5], v[38:39], v[40:41]
	v_pk_mul_f32 v[32:33], v[66:67], v[32:33] op_sel_hi:[0,1]
	v_add_f32_e32 v38, v38, v39
	v_pk_mul_f32 v[2:3], v[2:3], v[6:7]
	v_pk_fma_f32 v[18:19], v[4:5], v[18:19], v[30:31]
	v_add_f32_dpp v38, v38, v38 quad_perm:[1,0,3,2] row_mask:0xf bank_mask:0xf bound_ctrl:1
	ds_read_b128 v[100:103], v46 offset:36352
	v_pk_fma_f32 v[20:21], v[6:7], v[20:21], v[32:33]
	v_add_f32_dpp v38, v38, v38 quad_perm:[2,3,0,1] row_mask:0xf bank_mask:0xf bound_ctrl:1
	v_pk_fma_f32 v[0:1], v[0:1], v[4:5], v[2:3]
	ds_read_b128 v[42:45], v46 offset:35584
	v_add_f32_dpp v38, v38, v38 row_half_mirror row_mask:0xf bank_mask:0xf bound_ctrl:1
	v_add_f32_e32 v0, v0, v1
	ds_write_b32 v50, v0 offset:5120
	v_add_f32_dpp v38, v38, v38 row_mirror row_mask:0xf bank_mask:0xf bound_ctrl:1
	v_pk_fma_f32 v[18:19], v[34:35], v[38:39], v[18:19] op_sel_hi:[1,0,1]
	v_pk_fma_f32 v[20:21], v[36:37], v[38:39], v[20:21] op_sel_hi:[1,0,1]
	ds_read_b128 v[96:99], v46 offset:35840
	ds_read_b32 v110, v47 offset:36096
	ds_read_b128 v[104:107], v46 offset:36608
	ds_read_b128 v[92:95], v46 offset:35328
	s_waitcnt lgkmcnt(7)
; #define LAS __attribute__((address_space(3)))
; #define R4_ISSUE(cc, slot) do { const GAS float* g_ = gp + (size_t)(cc) * 2048; LAS float* l_ = ring + (slot) * 1536; _Pragma("unroll") for (int i_ = 0; i_ < 6; ++i_) \
;         __builtin_amdgcn_global_load_lds((const GAS unsigned*)(g_ + off[i_]), (LAS unsigned*)(l_ + i_ * 256), 16, 0, 0); } while (0)
; #define R4_LOAD(o, sb_) do { const LAS float* sb = (sb_); (o).r = *(const LAS f32x4*)(sb + cgp * 4); (o).w = *(const LAS f32x4*)(sb + 64 + cgp * 4); (o).k = *(const LAS f32x4*)(sb + 128 + cgp * 4); \
;         (o).a = *(const LAS f32x4*)(sb + 256 + cgp * 4); (o).b = *(const LAS f32x4*)(sb + 320 + cgp * 4); (o).vv = sb[192 + rq * 4 + rl]; asm volatile("" ::: "memory"); } while (0)
; __device__ __forceinline__ void rwkv_prompt_wave4(LAS float* ring, const GAS float* RW, int mbase, int h, int rq, GAS float* Sout, GAS float* YR, int lane) {
;     ...
;     for (int cc = 0; cc < 3; ++cc) R4_ISSUE(cc, cc);
;     float ykeep = 0.f;
;     R4Ops oA, oB, oC, oD;
;     asm volatile("s_waitcnt vmcnt(12)" ::: "memory");
;     R4_LOAD(oA, ring); R4_LOAD(oB, ring + 384);
;     for (int ci = 0; ci < NCH; ++ci) {
;         { const int cn = ci + 3; const int cl = cn < NCH ? cn : NCH - 1; R4_ISSUE(cl, cn % R4_NS); }
;         const LAS float* cb = ring + (ci % R4_NS) * 1536; const LAS float* nb = ring + ((ci + 1) % R4_NS) * 1536;
;         R4_LOAD(oC, cb + 768);  R4_STEP(oA, 0);
;         R4_LOAD(oD, cb + 1152); R4_STEP(oB, 1);
;         asm volatile("s_waitcnt vmcnt(12)" ::: "memory");
;         R4_LOAD(oA, nb);        R4_STEP(oC, 2);
;         R4_LOAD(oB, nb + 384);  R4_STEP(oD, 3);
;         if (cgp < 4) YR[(size_t)(mbase + ci * 4 + cgp) * 512 + h * 64 + rq * 4 + rl] = ykeep;
;     }
	v_pk_mul_f32 v[86:87], v[20:21], v[86:87]
	v_pk_mul_f32 v[80:81], v[108:109], v[80:81] op_sel_hi:[0,1]
	v_pk_fma_f32 v[84:85], v[18:19], v[84:85], v[86:87]
	v_pk_mul_f32 v[82:83], v[108:109], v[82:83] op_sel_hi:[0,1]
	v_add_f32_e32 v84, v84, v85
	v_pk_mul_f32 v[14:15], v[14:15], v[20:21]
	v_pk_fma_f32 v[76:77], v[18:19], v[76:77], v[80:81]
	v_add_f32_dpp v84, v84, v84 quad_perm:[1,0,3,2] row_mask:0xf bank_mask:0xf bound_ctrl:1
	ds_read_b128 v[26:29], v46 offset:37888
	v_pk_fma_f32 v[78:79], v[20:21], v[78:79], v[82:83]
	v_add_f32_dpp v84, v84, v84 quad_perm:[2,3,0,1] row_mask:0xf bank_mask:0xf bound_ctrl:1
	v_pk_fma_f32 v[12:13], v[12:13], v[18:19], v[14:15]
	ds_read_b128 v[4:7], v46 offset:37120
	v_add_f32_dpp v84, v84, v84 row_half_mirror row_mask:0xf bank_mask:0xf bound_ctrl:1
	v_add_f32_e32 v12, v12, v13
	ds_write_b32 v50, v12 offset:5376
	v_add_f32_dpp v84, v84, v84 row_mirror row_mask:0xf bank_mask:0xf bound_ctrl:1
	v_pk_fma_f32 v[76:77], v[88:89], v[84:85], v[76:77] op_sel_hi:[1,0,1]
	v_pk_fma_f32 v[78:79], v[90:91], v[84:85], v[78:79] op_sel_hi:[1,0,1]
	ds_read_b128 v[8:11], v46 offset:37376
	ds_read_b32 v64, v47 offset:37632
	ds_read_b128 v[22:25], v46 offset:38144
	ds_read_b128 v[0:3], v46 offset:36864
	s_waitcnt lgkmcnt(7)
	v_pk_mul_f32 v[102:103], v[78:79], v[102:103]
	v_pk_mul_f32 v[96:97], v[110:111], v[96:97] op_sel_hi:[0,1]
	v_pk_fma_f32 v[100:101], v[76:77], v[100:101], v[102:103]
	v_pk_mul_f32 v[98:99], v[110:111], v[98:99] op_sel_hi:[0,1]
	v_add_f32_e32 v100, v100, v101
	v_pk_mul_f32 v[74:75], v[74:75], v[78:79]
	v_pk_fma_f32 v[42:43], v[76:77], v[42:43], v[96:97]
	v_add_f32_dpp v100, v100, v100 quad_perm:[1,0,3,2] row_mask:0xf bank_mask:0xf bound_ctrl:1
	ds_read_b128 v[38:41], v46 offset:39424
	v_pk_fma_f32 v[44:45], v[78:79], v[44:45], v[98:99]
	v_add_f32_dpp v100, v100, v100 quad_perm:[2,3,0,1] row_mask:0xf bank_mask:0xf bound_ctrl:1
	v_pk_fma_f32 v[72:73], v[72:73], v[76:77], v[74:75]
	ds_read_b128 v[18:21], v46 offset:38656
	v_add_f32_dpp v100, v100, v100 row_half_mirror row_mask:0xf bank_mask:0xf bound_ctrl:1
	v_add_f32_e32 v72, v72, v73
	ds_write_b32 v50, v72 offset:5632
	v_add_f32_dpp v100, v100, v100 row_mirror row_mask:0xf bank_mask:0xf bound_ctrl:1
	v_pk_fma_f32 v[42:43], v[104:105], v[100:101], v[42:43] op_sel_hi:[1,0,1]
	v_pk_fma_f32 v[44:45], v[106:107], v[100:101], v[44:45] op_sel_hi:[1,0,1]
	ds_read_b128 v[30:33], v46 offset:38912
	ds_read_b32 v66, v47 offset:39168
	ds_read_b128 v[34:37], v46 offset:39680
	ds_read_b128 v[12:15], v46 offset:38400
	v_pk_mul_f32 v[94:95], v[94:95], v[44:45]
	s_nop 0
	v_pk_fma_f32 v[92:93], v[92:93], v[42:43], v[94:95]
	s_nop 0
	v_add_f32_e32 v92, v92, v93
	ds_write_b32 v50, v92 offset:5888
	s_waitcnt lgkmcnt(8)
	v_pk_mul_f32 v[28:29], v[44:45], v[28:29]
	v_pk_mul_f32 v[8:9], v[64:65], v[8:9] op_sel_hi:[0,1]
	v_pk_fma_f32 v[26:27], v[42:43], v[26:27], v[28:29]
	v_pk_mul_f32 v[10:11], v[64:65], v[10:11] op_sel_hi:[0,1]
	v_add_f32_e32 v26, v26, v27
	ds_read_b128 v[84:87], v46 offset:40960
	v_pk_fma_f32 v[4:5], v[42:43], v[4:5], v[8:9]
	v_add_f32_dpp v26, v26, v26 quad_perm:[1,0,3,2] row_mask:0xf bank_mask:0xf bound_ctrl:1
	ds_read_b128 v[76:79], v46 offset:40192
	v_pk_fma_f32 v[6:7], v[44:45], v[6:7], v[10:11]
	v_add_f32_dpp v26, v26, v26 quad_perm:[2,3,0,1] row_mask:0xf bank_mask:0xf bound_ctrl:1
	ds_read_b128 v[80:83], v46 offset:40448
	ds_read_b32 v108, v47 offset:40704
	v_add_f32_dpp v26, v26, v26 row_half_mirror row_mask:0xf bank_mask:0xf bound_ctrl:1
	ds_read_b128 v[88:91], v46 offset:41216
	ds_read_b128 v[72:75], v46 offset:39936
	v_add_f32_dpp v26, v26, v26 row_mirror row_mask:0xf bank_mask:0xf bound_ctrl:1
	v_pk_fma_f32 v[4:5], v[22:23], v[26:27], v[4:5] op_sel_hi:[1,0,1]
	v_pk_fma_f32 v[6:7], v[24:25], v[26:27], v[6:7] op_sel_hi:[1,0,1]
	s_nop 0
	s_waitcnt lgkmcnt(7)
	v_pk_mul_f32 v[40:41], v[6:7], v[40:41]
	v_pk_mul_f32 v[30:31], v[66:67], v[30:31] op_sel_hi:[0,1]
	v_pk_fma_f32 v[38:39], v[4:5], v[38:39], v[40:41]
	v_pk_mul_f32 v[32:33], v[66:67], v[32:33] op_sel_hi:[0,1]
	v_add_f32_e32 v38, v38, v39
	v_pk_mul_f32 v[2:3], v[2:3], v[6:7]
	v_pk_fma_f32 v[18:19], v[4:5], v[18:19], v[30:31]
	v_add_f32_dpp v38, v38, v38 quad_perm:[1,0,3,2] row_mask:0xf bank_mask:0xf bound_ctrl:1
	ds_read_b128 v[100:103], v46 offset:42496
	v_pk_fma_f32 v[20:21], v[6:7], v[20:21], v[32:33]
	v_add_f32_dpp v38, v38, v38 quad_perm:[2,3,0,1] row_mask:0xf bank_mask:0xf bound_ctrl:1
	v_pk_fma_f32 v[0:1], v[0:1], v[4:5], v[2:3]
	ds_read_b128 v[42:45], v46 offset:41728
	v_add_f32_dpp v38, v38, v38 row_half_mirror row_mask:0xf bank_mask:0xf bound_ctrl:1
	v_add_f32_e32 v0, v0, v1
	ds_write_b32 v50, v0 offset:6144
	v_add_f32_dpp v38, v38, v38 row_mirror row_mask:0xf bank_mask:0xf bound_ctrl:1
	v_pk_fma_f32 v[18:19], v[34:35], v[38:39], v[18:19] op_sel_hi:[1,0,1]
	v_pk_fma_f32 v[20:21], v[36:37], v[38:39], v[20:21] op_sel_hi:[1,0,1]
	ds_read_b128 v[96:99], v46 offset:41984
	ds_read_b32 v110, v47 offset:42240
	ds_read_b128 v[104:107], v46 offset:42752
	ds_read_b128 v[92:95], v46 offset:41472
	s_waitcnt lgkmcnt(7)
; #define LAS __attribute__((address_space(3)))
; #define R4_ISSUE(cc, slot) do { const GAS float* g_ = gp + (size_t)(cc) * 2048; LAS float* l_ = ring + (slot) * 1536; _Pragma("unroll") for (int i_ = 0; i_ < 6; ++i_) \
;         __builtin_amdgcn_global_load_lds((const GAS unsigned*)(g_ + off[i_]), (LAS unsigned*)(l_ + i_ * 256), 16, 0, 0); } while (0)
; #define R4_LOAD(o, sb_) do { const LAS float* sb = (sb_); (o).r = *(const LAS f32x4*)(sb + cgp * 4); (o).w = *(const LAS f32x4*)(sb + 64 + cgp * 4); (o).k = *(const LAS f32x4*)(sb + 128 + cgp * 4); \
;         (o).a = *(const LAS f32x4*)(sb + 256 + cgp * 4); (o).b = *(const LAS f32x4*)(sb + 320 + cgp * 4); (o).vv = sb[192 + rq * 4 + rl]; asm volatile("" ::: "memory"); } while (0)
; __device__ __forceinline__ void rwkv_prompt_wave4(LAS float* ring, const GAS float* RW, int mbase, int h, int rq, GAS float* Sout, GAS float* YR, int lane) {
;     ...
;     for (int cc = 0; cc < 3; ++cc) R4_ISSUE(cc, cc);
;     float ykeep = 0.f;
;     R4Ops oA, oB, oC, oD;
;     asm volatile("s_waitcnt vmcnt(12)" ::: "memory");
;     R4_LOAD(oA, ring); R4_LOAD(oB, ring + 384);
;     for (int ci = 0; ci < NCH; ++ci) {
;         { const int cn = ci + 3; const int cl = cn < NCH ? cn : NCH - 1; R4_ISSUE(cl, cn % R4_NS); }
;         const LAS float* cb = ring + (ci % R4_NS) * 1536; const LAS float* nb = ring + ((ci + 1) % R4_NS) * 1536;
;         R4_LOAD(oC, cb + 768);  R4_STEP(oA, 0);
;         R4_LOAD(oD, cb + 1152); R4_STEP(oB, 1);
;         asm volatile("s_waitcnt vmcnt(12)" ::: "memory");
;         R4_LOAD(oA, nb);        R4_STEP(oC, 2);
;         R4_LOAD(oB, nb + 384);  R4_STEP(oD, 3);
;         if (cgp < 4) YR[(size_t)(mbase + ci * 4 + cgp) * 512 + h * 64 + rq * 4 + rl] = ykeep;
;     }
	v_pk_mul_f32 v[86:87], v[20:21], v[86:87]
	v_pk_mul_f32 v[80:81], v[108:109], v[80:81] op_sel_hi:[0,1]
	v_pk_fma_f32 v[84:85], v[18:19], v[84:85], v[86:87]
	v_pk_mul_f32 v[82:83], v[108:109], v[82:83] op_sel_hi:[0,1]
	v_add_f32_e32 v84, v84, v85
	v_pk_mul_f32 v[14:15], v[14:15], v[20:21]
	v_pk_fma_f32 v[76:77], v[18:19], v[76:77], v[80:81]
	v_add_f32_dpp v84, v84, v84 quad_perm:[1,0,3,2] row_mask:0xf bank_mask:0xf bound_ctrl:1
	ds_read_b128 v[26:29], v46 offset:44032
	v_pk_fma_f32 v[78:79], v[20:21], v[78:79], v[82:83]
	v_add_f32_dpp v84, v84, v84 quad_perm:[2,3,0,1] row_mask:0xf bank_mask:0xf bound_ctrl:1
	v_pk_fma_f32 v[12:13], v[12:13], v[18:19], v[14:15]
	ds_read_b128 v[4:7], v46 offset:43264
	v_add_f32_dpp v84, v84, v84 row_half_mirror row_mask:0xf bank_mask:0xf bound_ctrl:1
	v_add_f32_e32 v12, v12, v13
	ds_write_b32 v50, v12 offset:6400
	v_add_f32_dpp v84, v84, v84 row_mirror row_mask:0xf bank_mask:0xf bound_ctrl:1
	v_pk_fma_f32 v[76:77], v[88:89], v[84:85], v[76:77] op_sel_hi:[1,0,1]
	v_pk_fma_f32 v[78:79], v[90:91], v[84:85], v[78:79] op_sel_hi:[1,0,1]
	ds_read_b128 v[8:11], v46 offset:43520
	ds_read_b32 v64, v47 offset:43776
	ds_read_b128 v[22:25], v46 offset:44288
	ds_read_b128 v[0:3], v46 offset:43008
	s_waitcnt lgkmcnt(7)
	v_pk_mul_f32 v[102:103], v[78:79], v[102:103]
	v_pk_mul_f32 v[96:97], v[110:111], v[96:97] op_sel_hi:[0,1]
	v_pk_fma_f32 v[100:101], v[76:77], v[100:101], v[102:103]
	v_pk_mul_f32 v[98:99], v[110:111], v[98:99] op_sel_hi:[0,1]
	v_add_f32_e32 v100, v100, v101
	v_pk_mul_f32 v[74:75], v[74:75], v[78:79]
	v_pk_fma_f32 v[42:43], v[76:77], v[42:43], v[96:97]
	v_add_f32_dpp v100, v100, v100 quad_perm:[1,0,3,2] row_mask:0xf bank_mask:0xf bound_ctrl:1
	ds_read_b128 v[38:41], v46 offset:45568
	v_pk_fma_f32 v[44:45], v[78:79], v[44:45], v[98:99]
	v_add_f32_dpp v100, v100, v100 quad_perm:[2,3,0,1] row_mask:0xf bank_mask:0xf bound_ctrl:1
	v_pk_fma_f32 v[72:73], v[72:73], v[76:77], v[74:75]
	ds_read_b128 v[18:21], v46 offset:44800
	v_add_f32_dpp v100, v100, v100 row_half_mirror row_mask:0xf bank_mask:0xf bound_ctrl:1
	v_add_f32_e32 v72, v72, v73
	ds_write_b32 v50, v72 offset:6656
	v_add_f32_dpp v100, v100, v100 row_mirror row_mask:0xf bank_mask:0xf bound_ctrl:1
	v_pk_fma_f32 v[42:43], v[104:105], v[100:101], v[42:43] op_sel_hi:[1,0,1]
	v_pk_fma_f32 v[44:45], v[106:107], v[100:101], v[44:45] op_sel_hi:[1,0,1]
	ds_read_b128 v[30:33], v46 offset:45056
	ds_read_b32 v66, v47 offset:45312
	ds_read_b128 v[34:37], v46 offset:45824
	ds_read_b128 v[12:15], v46 offset:44544
	v_pk_mul_f32 v[94:95], v[94:95], v[44:45]
	s_nop 0
	v_pk_fma_f32 v[92:93], v[92:93], v[42:43], v[94:95]
	s_nop 0
	v_add_f32_e32 v92, v92, v93
	ds_write_b32 v50, v92 offset:6912
	s_waitcnt lgkmcnt(8)
	v_pk_mul_f32 v[28:29], v[44:45], v[28:29]
	v_pk_mul_f32 v[8:9], v[64:65], v[8:9] op_sel_hi:[0,1]
	v_pk_fma_f32 v[26:27], v[42:43], v[26:27], v[28:29]
	v_pk_mul_f32 v[10:11], v[64:65], v[10:11] op_sel_hi:[0,1]
	v_add_f32_e32 v26, v26, v27
	ds_read_b128 v[84:87], v46 offset:47104
	v_pk_fma_f32 v[4:5], v[42:43], v[4:5], v[8:9]
	v_add_f32_dpp v26, v26, v26 quad_perm:[1,0,3,2] row_mask:0xf bank_mask:0xf bound_ctrl:1
	ds_read_b128 v[76:79], v46 offset:46336
	v_pk_fma_f32 v[6:7], v[44:45], v[6:7], v[10:11]
	v_add_f32_dpp v26, v26, v26 quad_perm:[2,3,0,1] row_mask:0xf bank_mask:0xf bound_ctrl:1
	ds_read_b128 v[80:83], v46 offset:46592
	ds_read_b32 v108, v47 offset:46848
	v_add_f32_dpp v26, v26, v26 row_half_mirror row_mask:0xf bank_mask:0xf bound_ctrl:1
	ds_read_b128 v[88:91], v46 offset:47360
	ds_read_b128 v[72:75], v46 offset:46080
	v_add_f32_dpp v26, v26, v26 row_mirror row_mask:0xf bank_mask:0xf bound_ctrl:1
	v_pk_fma_f32 v[4:5], v[22:23], v[26:27], v[4:5] op_sel_hi:[1,0,1]
	v_pk_fma_f32 v[6:7], v[24:25], v[26:27], v[6:7] op_sel_hi:[1,0,1]
	s_nop 0
	s_waitcnt lgkmcnt(7)
; #define LAS __attribute__((address_space(3)))
; #define R4_ISSUE(cc, slot) do { const GAS float* g_ = gp + (size_t)(cc) * 2048; LAS float* l_ = ring + (slot) * 1536; _Pragma("unroll") for (int i_ = 0; i_ < 6; ++i_) \
;         __builtin_amdgcn_global_load_lds((const GAS unsigned*)(g_ + off[i_]), (LAS unsigned*)(l_ + i_ * 256), 16, 0, 0); } while (0)
; #define R4_LOAD(o, sb_) do { const LAS float* sb = (sb_); (o).r = *(const LAS f32x4*)(sb + cgp * 4); (o).w = *(const LAS f32x4*)(sb + 64 + cgp * 4); (o).k = *(const LAS f32x4*)(sb + 128 + cgp * 4); \
;         (o).a = *(const LAS f32x4*)(sb + 256 + cgp * 4); (o).b = *(const LAS f32x4*)(sb + 320 + cgp * 4); (o).vv = sb[192 + rq * 4 + rl]; asm volatile("" ::: "memory"); } while (0)
; __device__ __forceinline__ void rwkv_prompt_wave4(LAS float* ring, const GAS float* RW, int mbase, int h, int rq, GAS float* Sout, GAS float* YR, int lane) {
;     ...
;     for (int cc = 0; cc < 3; ++cc) R4_ISSUE(cc, cc);
;     float ykeep = 0.f;
;     R4Ops oA, oB, oC, oD;
;     asm volatile("s_waitcnt vmcnt(12)" ::: "memory");
;     R4_LOAD(oA, ring); R4_LOAD(oB, ring + 384);
;     for (int ci = 0; ci < NCH; ++ci) {
;         { const int cn = ci + 3; const int cl = cn < NCH ? cn : NCH - 1; R4_ISSUE(cl, cn % R4_NS); }
;         const LAS float* cb = ring + (ci % R4_NS) * 1536; const LAS float* nb = ring + ((ci + 1) % R4_NS) * 1536;
;         R4_LOAD(oC, cb + 768);  R4_STEP(oA, 0);
;         R4_LOAD(oD, cb + 1152); R4_STEP(oB, 1);
;         asm volatile("s_waitcnt vmcnt(12)" ::: "memory");
;         R4_LOAD(oA, nb);        R4_STEP(oC, 2);
;         R4_LOAD(oB, nb + 384);  R4_STEP(oD, 3);
;         if (cgp < 4) YR[(size_t)(mbase + ci * 4 + cgp) * 512 + h * 64 + rq * 4 + rl] = ykeep;
;     }
	v_pk_mul_f32 v[40:41], v[6:7], v[40:41]
	v_pk_mul_f32 v[30:31], v[66:67], v[30:31] op_sel_hi:[0,1]
	v_pk_fma_f32 v[38:39], v[4:5], v[38:39], v[40:41]
	v_pk_mul_f32 v[32:33], v[66:67], v[32:33] op_sel_hi:[0,1]
	v_add_f32_e32 v38, v38, v39
	v_pk_mul_f32 v[2:3], v[2:3], v[6:7]
	v_pk_fma_f32 v[18:19], v[4:5], v[18:19], v[30:31]
	v_add_f32_dpp v38, v38, v38 quad_perm:[1,0,3,2] row_mask:0xf bank_mask:0xf bound_ctrl:1
	ds_read_b128 v[100:103], v46 offset:48640
	v_pk_fma_f32 v[20:21], v[6:7], v[20:21], v[32:33]
	v_add_f32_dpp v38, v38, v38 quad_perm:[2,3,0,1] row_mask:0xf bank_mask:0xf bound_ctrl:1
	v_pk_fma_f32 v[0:1], v[0:1], v[4:5], v[2:3]
	ds_read_b128 v[42:45], v46 offset:47872
	v_add_f32_dpp v38, v38, v38 row_half_mirror row_mask:0xf bank_mask:0xf bound_ctrl:1
	v_add_f32_e32 v0, v0, v1
	ds_write_b32 v50, v0 offset:7168
	v_add_f32_dpp v38, v38, v38 row_mirror row_mask:0xf bank_mask:0xf bound_ctrl:1
	v_pk_fma_f32 v[18:19], v[34:35], v[38:39], v[18:19] op_sel_hi:[1,0,1]
	v_pk_fma_f32 v[20:21], v[36:37], v[38:39], v[20:21] op_sel_hi:[1,0,1]
	ds_read_b128 v[96:99], v46 offset:48128
	ds_read_b32 v110, v47 offset:48384
	ds_read_b128 v[104:107], v46 offset:48896
	ds_read_b128 v[92:95], v46 offset:47616
	s_waitcnt lgkmcnt(7)
	v_pk_mul_f32 v[86:87], v[20:21], v[86:87]
	v_pk_mul_f32 v[80:81], v[108:109], v[80:81] op_sel_hi:[0,1]
	v_pk_fma_f32 v[84:85], v[18:19], v[84:85], v[86:87]
	v_pk_mul_f32 v[82:83], v[108:109], v[82:83] op_sel_hi:[0,1]
	v_add_f32_e32 v84, v84, v85
	v_pk_mul_f32 v[14:15], v[14:15], v[20:21]
	v_pk_fma_f32 v[76:77], v[18:19], v[76:77], v[80:81]
	v_add_f32_dpp v84, v84, v84 quad_perm:[1,0,3,2] row_mask:0xf bank_mask:0xf bound_ctrl:1
	ds_read_b128 v[26:29], v67 offset:1024
	v_pk_fma_f32 v[78:79], v[20:21], v[78:79], v[82:83]
	v_add_f32_dpp v84, v84, v84 quad_perm:[2,3,0,1] row_mask:0xf bank_mask:0xf bound_ctrl:1
	v_pk_fma_f32 v[12:13], v[12:13], v[18:19], v[14:15]
	ds_read_b128 v[4:7], v67 offset:256
	v_add_f32_dpp v84, v84, v84 row_half_mirror row_mask:0xf bank_mask:0xf bound_ctrl:1
	v_add_f32_e32 v12, v12, v13
	ds_write_b32 v50, v12 offset:7424
	v_add_f32_dpp v84, v84, v84 row_mirror row_mask:0xf bank_mask:0xf bound_ctrl:1
	v_pk_fma_f32 v[76:77], v[88:89], v[84:85], v[76:77] op_sel_hi:[1,0,1]
	v_pk_fma_f32 v[78:79], v[90:91], v[84:85], v[78:79] op_sel_hi:[1,0,1]
	ds_read_b128 v[8:11], v67 offset:512
	ds_read_b32 v64, v70 offset:768
	ds_read_b128 v[22:25], v67 offset:1280
	ds_read_b128 v[0:3], v67 offset:0
	s_waitcnt lgkmcnt(7)
	v_pk_mul_f32 v[102:103], v[78:79], v[102:103]
	v_pk_mul_f32 v[96:97], v[110:111], v[96:97] op_sel_hi:[0,1]
	v_pk_fma_f32 v[100:101], v[76:77], v[100:101], v[102:103]
	v_pk_mul_f32 v[98:99], v[110:111], v[98:99] op_sel_hi:[0,1]
	v_add_f32_e32 v100, v100, v101
	v_pk_mul_f32 v[74:75], v[74:75], v[78:79]
	v_pk_fma_f32 v[42:43], v[76:77], v[42:43], v[96:97]
	v_add_f32_dpp v100, v100, v100 quad_perm:[1,0,3,2] row_mask:0xf bank_mask:0xf bound_ctrl:1
	ds_read_b128 v[38:41], v67 offset:2560
	v_pk_fma_f32 v[44:45], v[78:79], v[44:45], v[98:99]
	v_add_f32_dpp v100, v100, v100 quad_perm:[2,3,0,1] row_mask:0xf bank_mask:0xf bound_ctrl:1
	v_pk_fma_f32 v[72:73], v[72:73], v[76:77], v[74:75]
	ds_read_b128 v[18:21], v67 offset:1792
	v_add_f32_dpp v100, v100, v100 row_half_mirror row_mask:0xf bank_mask:0xf bound_ctrl:1
	v_add_f32_e32 v72, v72, v73
	ds_write_b32 v50, v72 offset:7680
	v_add_f32_dpp v100, v100, v100 row_mirror row_mask:0xf bank_mask:0xf bound_ctrl:1
	v_pk_fma_f32 v[42:43], v[104:105], v[100:101], v[42:43] op_sel_hi:[1,0,1]
	v_pk_fma_f32 v[44:45], v[106:107], v[100:101], v[44:45] op_sel_hi:[1,0,1]
	ds_read_b128 v[30:33], v67 offset:2048
	ds_read_b32 v66, v70 offset:2304
	ds_read_b128 v[34:37], v67 offset:2816
	ds_read_b128 v[12:15], v67 offset:1536
	v_pk_mul_f32 v[94:95], v[94:95], v[44:45]
	s_nop 0
	v_pk_fma_f32 v[92:93], v[92:93], v[42:43], v[94:95]
	s_nop 0
	v_add_f32_e32 v92, v92, v93
	ds_write_b32 v50, v92 offset:7936
	s_add_i32 s21, s21, 16
	s_cmpk_lg_u32 s21, 0x200
	s_cbranch_scc1 .LBB0_707
	s_branch .LBB0_704
